# GEMM mainloops: per-segment s_setprio flips removed (all four loops)
# speedup vs baseline: 1.0122x; 1.0115x over previous
; #define PG8_STAGE(bufoff, gbase, voff) do { _Pragma("unroll") for (int _i = 0; _i < 2; ++_i) \
;         __builtin_amdgcn_global_load_lds((const unsigned*)((const char*)(gbase) + (voff)[_i]), (PG8_LAS unsigned*)(lds + (bufoff) + ldsw + _i * 8192), 16, 0, 0); } while (0)
; #define PG8_LDA(dst, b, h) do { _Pragma("unroll") for (int m = 0; m < 4; ++m) _Pragma("unroll") for (int k = 0; k < 2; ++k) dst[m][k] = *(const PG8_LAS bf16x8*)(lds + PG8_SA(b, h) + aoff + m * 2048 + k * 1024); } while (0)
; #define PG8_LDB(dst, b, h) do { _Pragma("unroll") for (int n = 0; n < 2; ++n) _Pragma("unroll") for (int k = 0; k < 2; ++k) dst[n][k] = *(const PG8_LAS bf16x8*)(lds + PG8_SB(b, h) + boff + n * 2048 + k * 1024); } while (0)
; #define PG8_MMA(ai, bj, At, Bt) do { __builtin_amdgcn_s_setprio(1); _Pragma("unroll") for (int m = 0; m < 4; ++m) _Pragma("unroll") for (int n = 0; n < 2; ++n) _Pragma("unroll") for (int k = 0; k < 2; ++k) \
;         acc[ai][bj][m][n] = __builtin_amdgcn_mfma_f32_16x16x32_bf16(Bt[n][k], At[m][k], acc[ai][bj][m][n], 0, 0, 0); __builtin_amdgcn_s_setprio(0); } while (0)
; #define PG8_BAR __builtin_amdgcn_s_barrier()
; template <class Epi, class Sched, bool ALIGN_EPI = false, bool SP2 = false>
; __device__ __forceinline__ void gemm_phase(PG8_LAS unsigned char* lds, const Gemm g, const Sched& S, const Epi& E) {
;     ...
;             if constexpr (SP2) {
;             PG8_LDB(B0, 0, 0); PG8_LDB(B1, 0, 1); PG8_SCHED; PG8_LDA(At, 0, 0); PG8_STAGE(PG8_SA(1, 1), a1 + hstep, voffA);
;             PG8_WAIT_V(8); PG8_WAIT_L(0); PG8_BAR; PG8_MMA(0, 0, At, B0); PG8_MMA(0, 1, At, B1); PG8_BAR; PG8_SCHED;
;             PG8_LDA(At, 0, 1); PG8_STAGE(PG8_SB(0, 0), b2, voffB); PG8_STAGE(PG8_SB(0, 1), b2 + hstep, voffB); PG8_STAGE(PG8_SA(0, 0), a2, voffA);
;             PG8_WAIT_V(8); PG8_WAIT_L(0); PG8_BAR; PG8_MMA(1, 0, At, B0); PG8_MMA(1, 1, At, B1); PG8_BAR; PG8_SCHED;
;             PG8_LDB(B0, 1, 0); PG8_LDB(B1, 1, 1); PG8_SCHED; PG8_LDA(At, 1, 0); PG8_STAGE(PG8_SA(0, 1), a2 + hstep, voffA);
;             PG8_WAIT_V(8); PG8_WAIT_L(0); PG8_BAR; PG8_MMA(0, 0, At, B0); PG8_MMA(0, 1, At, B1); PG8_BAR; PG8_SCHED;
;             PG8_LDA(At, 1, 1); PG8_STAGE(PG8_SB(1, 0), b3, voffB); PG8_STAGE(PG8_SB(1, 1), b3 + hstep, voffB); PG8_STAGE(PG8_SA(1, 0), a3, voffA);
;             PG8_WAIT_V(8); PG8_WAIT_L(0); PG8_BAR; PG8_MMA(1, 0, At, B0); PG8_MMA(1, 1, At, B1); PG8_BAR; PG8_SCHED;
.LBB0_237:
	s_add_u32 s44, s42, 0xfffc0080
	s_addc_u32 s45, s43, -1
	s_add_i32 s63, 0, 0x10000
	s_cmp_eq_u32 s62, 12
	s_cselect_b32 s47, s13, s45
	s_cselect_b32 s46, s19, s44
	v_add_u32_e32 v141, s63, v145
	s_cselect_b32 s45, s11, s61
	s_cselect_b32 s44, s41, s60
	s_add_i32 s66, 0, 0x14000
	ds_read_b128 v[150:153], v141
	ds_read_b128 v[170:173], v141 offset:1024
	ds_read_b128 v[174:177], v141 offset:2048
	ds_read_b128 v[178:181], v141 offset:3072
	v_add_u32_e32 v141, s66, v145
	ds_read_b128 v[182:185], v141
	ds_read_b128 v[186:189], v141 offset:1024
	ds_read_b128 v[190:193], v141 offset:2048
	ds_read_b128 v[194:197], v141 offset:3072
	v_lshl_add_u64 v[154:155], s[42:43], 0, v[136:137]
	s_add_i32 m0, s49, 0xc000
	ds_read_b128 v[198:201], v149
	ds_read_b128 v[202:205], v149 offset:1024
	ds_read_b128 v[206:209], v149 offset:2048
	ds_read_b128 v[210:213], v149 offset:3072
	ds_read_b128 v[214:217], v149 offset:4096
	ds_read_b128 v[218:221], v149 offset:5120
	ds_read_b128 v[222:225], v149 offset:6144
	ds_read_b128 v[226:229], v149 offset:7168
	global_load_lds_dwordx4 v[154:155], off
	v_lshl_add_u64 v[154:155], s[42:43], 0, v[138:139]
	s_add_i32 m0, s49, 0xe000
	s_nop 0
	global_load_lds_dwordx4 v[154:155], off
	s_waitcnt vmcnt(8)
	s_waitcnt lgkmcnt(0)
	s_barrier
	s_waitcnt lgkmcnt(0)
	v_mfma_f32_16x16x32_bf16 v[124:127], v[150:153], v[198:201], v[124:127]
	v_mfma_f32_16x16x32_bf16 v[120:123], v[174:177], v[198:201], v[120:123]
	v_mfma_f32_16x16x32_bf16 v[108:111], v[150:153], v[206:209], v[108:111]
	v_mfma_f32_16x16x32_bf16 v[104:107], v[174:177], v[206:209], v[104:107]
	v_mfma_f32_16x16x32_bf16 v[96:99], v[150:153], v[214:217], v[96:99]
	v_mfma_f32_16x16x32_bf16 v[88:91], v[174:177], v[214:217], v[88:91]
	v_mfma_f32_16x16x32_bf16 v[80:83], v[150:153], v[222:225], v[80:83]
	v_mfma_f32_16x16x32_bf16 v[72:75], v[174:177], v[222:225], v[72:75]
	v_mfma_f32_16x16x32_bf16 v[124:127], v[170:173], v[202:205], v[124:127]
	v_mfma_f32_16x16x32_bf16 v[120:123], v[178:181], v[202:205], v[120:123]
	v_mfma_f32_16x16x32_bf16 v[108:111], v[170:173], v[210:213], v[108:111]
	v_mfma_f32_16x16x32_bf16 v[104:107], v[178:181], v[210:213], v[104:107]
	v_mfma_f32_16x16x32_bf16 v[96:99], v[170:173], v[218:221], v[96:99]
	v_mfma_f32_16x16x32_bf16 v[88:91], v[178:181], v[218:221], v[88:91]
	v_mfma_f32_16x16x32_bf16 v[80:83], v[170:173], v[226:229], v[80:83]
	v_mfma_f32_16x16x32_bf16 v[72:75], v[178:181], v[226:229], v[72:75]
	v_mfma_f32_16x16x32_bf16 v[116:119], v[182:185], v[198:201], v[116:119]
	v_mfma_f32_16x16x32_bf16 v[112:115], v[190:193], v[198:201], v[112:115]
	v_mfma_f32_16x16x32_bf16 v[100:103], v[182:185], v[206:209], v[100:103]
	v_mfma_f32_16x16x32_bf16 v[92:95], v[190:193], v[206:209], v[92:95]
	v_mfma_f32_16x16x32_bf16 v[84:87], v[182:185], v[214:217], v[84:87]
	v_mfma_f32_16x16x32_bf16 v[76:79], v[190:193], v[214:217], v[76:79]
	v_mfma_f32_16x16x32_bf16 v[68:71], v[182:185], v[222:225], v[68:71]
	v_mfma_f32_16x16x32_bf16 v[64:67], v[190:193], v[222:225], v[64:67]
	v_mfma_f32_16x16x32_bf16 v[116:119], v[186:189], v[202:205], v[116:119]
	v_mfma_f32_16x16x32_bf16 v[112:115], v[194:197], v[202:205], v[112:115]
	v_mfma_f32_16x16x32_bf16 v[100:103], v[186:189], v[210:213], v[100:103]
	v_mfma_f32_16x16x32_bf16 v[92:95], v[194:197], v[210:213], v[92:95]
	v_mfma_f32_16x16x32_bf16 v[84:87], v[186:189], v[218:221], v[84:87]
	v_mfma_f32_16x16x32_bf16 v[76:79], v[194:197], v[218:221], v[76:79]
	v_mfma_f32_16x16x32_bf16 v[68:71], v[186:189], v[226:229], v[68:71]
	v_mfma_f32_16x16x32_bf16 v[64:67], v[194:197], v[226:229], v[64:67]
	s_barrier
	s_add_i32 s63, s63, s34
	v_lshl_add_u64 v[154:155], s[44:45], 0, v[132:133]
	s_mov_b32 m0, s63
	ds_read_b128 v[198:201], v149 offset:16384
	ds_read_b128 v[202:205], v149 offset:17408
	ds_read_b128 v[206:209], v149 offset:18432
	ds_read_b128 v[210:213], v149 offset:19456
	ds_read_b128 v[214:217], v149 offset:20480
	ds_read_b128 v[218:221], v149 offset:21504
	ds_read_b128 v[222:225], v149 offset:22528
	ds_read_b128 v[226:229], v149 offset:23552
	global_load_lds_dwordx4 v[154:155], off
	s_add_i32 m0, s63, 0x2000
	s_add_u32 s64, s44, 0x40000
	v_lshl_add_u64 v[236:237], s[44:45], 0, v[128:129]
	s_addc_u32 s65, s45, 0
	s_add_i32 s63, s66, s34
	global_load_lds_dwordx4 v[236:237], off
	v_lshl_add_u64 v[238:239], s[64:65], 0, v[132:133]
	s_mov_b32 m0, s63
	v_lshl_add_u64 v[240:241], s[46:47], 0, v[130:131]
	global_load_lds_dwordx4 v[238:239], off
	v_lshl_add_u64 v[238:239], s[64:65], 0, v[128:129]
	s_add_i32 m0, s63, 0x2000
	s_nop 0
	global_load_lds_dwordx4 v[238:239], off
	v_lshl_add_u64 v[238:239], s[46:47], 0, v[134:135]
	s_mov_b32 m0, s49
	s_nop 0
	global_load_lds_dwordx4 v[238:239], off
	s_mov_b32 m0, s50
	s_nop 0
	global_load_lds_dwordx4 v[240:241], off
	s_waitcnt vmcnt(8)
	s_waitcnt lgkmcnt(0)
	s_barrier
; #define PG8_STAGE(bufoff, gbase, voff) do { _Pragma("unroll") for (int _i = 0; _i < 2; ++_i) \
;         __builtin_amdgcn_global_load_lds((const unsigned*)((const char*)(gbase) + (voff)[_i]), (PG8_LAS unsigned*)(lds + (bufoff) + ldsw + _i * 8192), 16, 0, 0); } while (0)
; #define PG8_LDA(dst, b, h) do { _Pragma("unroll") for (int m = 0; m < 4; ++m) _Pragma("unroll") for (int k = 0; k < 2; ++k) dst[m][k] = *(const PG8_LAS bf16x8*)(lds + PG8_SA(b, h) + aoff + m * 2048 + k * 1024); } while (0)
; #define PG8_LDB(dst, b, h) do { _Pragma("unroll") for (int n = 0; n < 2; ++n) _Pragma("unroll") for (int k = 0; k < 2; ++k) dst[n][k] = *(const PG8_LAS bf16x8*)(lds + PG8_SB(b, h) + boff + n * 2048 + k * 1024); } while (0)
; #define PG8_MMA(ai, bj, At, Bt) do { __builtin_amdgcn_s_setprio(1); _Pragma("unroll") for (int m = 0; m < 4; ++m) _Pragma("unroll") for (int n = 0; n < 2; ++n) _Pragma("unroll") for (int k = 0; k < 2; ++k) \
;         acc[ai][bj][m][n] = __builtin_amdgcn_mfma_f32_16x16x32_bf16(Bt[n][k], At[m][k], acc[ai][bj][m][n], 0, 0, 0); __builtin_amdgcn_s_setprio(0); } while (0)
; #define PG8_WAIT_V(n) asm volatile("s_waitcnt vmcnt(" #n ")" ::: "memory")
; #define PG8_WAIT_L(n) asm volatile("s_waitcnt lgkmcnt(" #n ")" ::: "memory")
; #define PG8_BAR __builtin_amdgcn_s_barrier()
; #define PG8_SCHED __builtin_amdgcn_sched_barrier(0)
; template <class Epi, class Sched, bool ALIGN_EPI = false, bool SP2 = false>
; __device__ __forceinline__ void gemm_phase(PG8_LAS unsigned char* lds, const Gemm g, const Sched& S, const Epi& E) {
;     ...
;             PG8_WAIT_V(8); PG8_WAIT_L(0); PG8_BAR; PG8_MMA(0, 0, At, B0); PG8_MMA(0, 1, At, B1); PG8_BAR; PG8_SCHED;
;             PG8_LDA(At, 0, 1); PG8_STAGE(PG8_SB(0, 0), b2, voffB); PG8_STAGE(PG8_SB(0, 1), b2 + hstep, voffB); PG8_STAGE(PG8_SA(0, 0), a2, voffA);
;             PG8_WAIT_V(8); PG8_WAIT_L(0); PG8_BAR; PG8_MMA(1, 0, At, B0); PG8_MMA(1, 1, At, B1); PG8_BAR; PG8_SCHED;
;             PG8_LDB(B0, 1, 0); PG8_LDB(B1, 1, 1); PG8_SCHED; PG8_LDA(At, 1, 0); PG8_STAGE(PG8_SA(0, 1), a2 + hstep, voffA);
;             PG8_WAIT_V(8); PG8_WAIT_L(0); PG8_BAR; PG8_MMA(0, 0, At, B0); PG8_MMA(0, 1, At, B1); PG8_BAR; PG8_SCHED;
	s_waitcnt lgkmcnt(0)
	v_mfma_f32_16x16x32_bf16 v[60:63], v[150:153], v[198:201], v[60:63]
	v_mfma_f32_16x16x32_bf16 v[56:59], v[174:177], v[198:201], v[56:59]
	v_mfma_f32_16x16x32_bf16 v[44:47], v[150:153], v[206:209], v[44:47]
	v_mfma_f32_16x16x32_bf16 v[40:43], v[174:177], v[206:209], v[40:43]
	v_mfma_f32_16x16x32_bf16 v[32:35], v[150:153], v[214:217], v[32:35]
	v_mfma_f32_16x16x32_bf16 v[24:27], v[174:177], v[214:217], v[24:27]
	v_mfma_f32_16x16x32_bf16 v[16:19], v[150:153], v[222:225], v[16:19]
	v_mfma_f32_16x16x32_bf16 v[8:11], v[174:177], v[222:225], v[8:11]
	v_mfma_f32_16x16x32_bf16 v[60:63], v[170:173], v[202:205], v[60:63]
	v_mfma_f32_16x16x32_bf16 v[56:59], v[178:181], v[202:205], v[56:59]
	v_mfma_f32_16x16x32_bf16 v[44:47], v[170:173], v[210:213], v[44:47]
	v_mfma_f32_16x16x32_bf16 v[40:43], v[178:181], v[210:213], v[40:43]
	v_mfma_f32_16x16x32_bf16 v[32:35], v[170:173], v[218:221], v[32:35]
	v_mfma_f32_16x16x32_bf16 v[24:27], v[178:181], v[218:221], v[24:27]
	v_mfma_f32_16x16x32_bf16 v[16:19], v[170:173], v[226:229], v[16:19]
	v_mfma_f32_16x16x32_bf16 v[8:11], v[178:181], v[226:229], v[8:11]
	v_mfma_f32_16x16x32_bf16 v[52:55], v[182:185], v[198:201], v[52:55]
	v_mfma_f32_16x16x32_bf16 v[48:51], v[190:193], v[198:201], v[48:51]
	v_mfma_f32_16x16x32_bf16 v[36:39], v[182:185], v[206:209], v[36:39]
	v_mfma_f32_16x16x32_bf16 v[28:31], v[190:193], v[206:209], v[28:31]
	v_mfma_f32_16x16x32_bf16 v[20:23], v[182:185], v[214:217], v[20:23]
	v_mfma_f32_16x16x32_bf16 v[12:15], v[190:193], v[214:217], v[12:15]
	v_mfma_f32_16x16x32_bf16 v[4:7], v[182:185], v[222:225], v[4:7]
	v_mfma_f32_16x16x32_bf16 v[0:3], v[190:193], v[222:225], v[0:3]
	v_mfma_f32_16x16x32_bf16 v[52:55], v[186:189], v[202:205], v[52:55]
	v_mfma_f32_16x16x32_bf16 v[48:51], v[194:197], v[202:205], v[48:51]
	v_mfma_f32_16x16x32_bf16 v[36:39], v[186:189], v[210:213], v[36:39]
	v_mfma_f32_16x16x32_bf16 v[28:31], v[194:197], v[210:213], v[28:31]
	v_mfma_f32_16x16x32_bf16 v[20:23], v[186:189], v[218:221], v[20:23]
	v_mfma_f32_16x16x32_bf16 v[12:15], v[194:197], v[218:221], v[12:15]
	v_mfma_f32_16x16x32_bf16 v[4:7], v[186:189], v[226:229], v[4:7]
	v_mfma_f32_16x16x32_bf16 v[0:3], v[194:197], v[226:229], v[0:3]
	s_barrier
	s_add_i32 s63, 0, 0x18000
	v_add_u32_e32 v141, s63, v145
	s_add_i32 s64, 0, 0x1c000
	ds_read_b128 v[150:153], v141
	ds_read_b128 v[170:173], v141 offset:1024
	ds_read_b128 v[174:177], v141 offset:2048
	ds_read_b128 v[178:181], v141 offset:3072
	v_add_u32_e32 v141, s64, v145
	ds_read_b128 v[182:185], v141
	ds_read_b128 v[186:189], v141 offset:1024
	ds_read_b128 v[190:193], v141 offset:2048
	ds_read_b128 v[194:197], v141 offset:3072
	s_add_u32 s46, s46, 0x40000
	s_addc_u32 s47, s47, 0
	s_mov_b32 m0, s51
	v_lshl_add_u64 v[242:243], s[46:47], 0, v[134:135]
	ds_read_b128 v[198:201], v149 offset:32768
	ds_read_b128 v[202:205], v149 offset:33792
	ds_read_b128 v[206:209], v149 offset:34816
	ds_read_b128 v[210:213], v149 offset:35840
	ds_read_b128 v[214:217], v149 offset:36864
	ds_read_b128 v[218:221], v149 offset:37888
	ds_read_b128 v[222:225], v149 offset:38912
	ds_read_b128 v[226:229], v149 offset:39936
	global_load_lds_dwordx4 v[242:243], off
	v_lshl_add_u64 v[242:243], s[46:47], 0, v[130:131]
	s_mov_b32 m0, s52
	s_nop 0
	global_load_lds_dwordx4 v[242:243], off
	s_waitcnt vmcnt(8)
	s_waitcnt lgkmcnt(0)
	s_barrier
	s_waitcnt lgkmcnt(0)
	v_mfma_f32_16x16x32_bf16 v[124:127], v[150:153], v[198:201], v[124:127]
	v_mfma_f32_16x16x32_bf16 v[120:123], v[174:177], v[198:201], v[120:123]
	v_mfma_f32_16x16x32_bf16 v[108:111], v[150:153], v[206:209], v[108:111]
	v_mfma_f32_16x16x32_bf16 v[104:107], v[174:177], v[206:209], v[104:107]
	v_mfma_f32_16x16x32_bf16 v[96:99], v[150:153], v[214:217], v[96:99]
	v_mfma_f32_16x16x32_bf16 v[88:91], v[174:177], v[214:217], v[88:91]
	v_mfma_f32_16x16x32_bf16 v[80:83], v[150:153], v[222:225], v[80:83]
	v_mfma_f32_16x16x32_bf16 v[72:75], v[174:177], v[222:225], v[72:75]
	v_mfma_f32_16x16x32_bf16 v[124:127], v[170:173], v[202:205], v[124:127]
	v_mfma_f32_16x16x32_bf16 v[120:123], v[178:181], v[202:205], v[120:123]
	v_mfma_f32_16x16x32_bf16 v[108:111], v[170:173], v[210:213], v[108:111]
	v_mfma_f32_16x16x32_bf16 v[104:107], v[178:181], v[210:213], v[104:107]
	v_mfma_f32_16x16x32_bf16 v[96:99], v[170:173], v[218:221], v[96:99]
	v_mfma_f32_16x16x32_bf16 v[88:91], v[178:181], v[218:221], v[88:91]
	v_mfma_f32_16x16x32_bf16 v[80:83], v[170:173], v[226:229], v[80:83]
	v_mfma_f32_16x16x32_bf16 v[72:75], v[178:181], v[226:229], v[72:75]
	v_mfma_f32_16x16x32_bf16 v[116:119], v[182:185], v[198:201], v[116:119]
	v_mfma_f32_16x16x32_bf16 v[112:115], v[190:193], v[198:201], v[112:115]
	v_mfma_f32_16x16x32_bf16 v[100:103], v[182:185], v[206:209], v[100:103]
	v_mfma_f32_16x16x32_bf16 v[92:95], v[190:193], v[206:209], v[92:95]
	v_mfma_f32_16x16x32_bf16 v[84:87], v[182:185], v[214:217], v[84:87]
	v_mfma_f32_16x16x32_bf16 v[76:79], v[190:193], v[214:217], v[76:79]
	v_mfma_f32_16x16x32_bf16 v[68:71], v[182:185], v[222:225], v[68:71]
	v_mfma_f32_16x16x32_bf16 v[64:67], v[190:193], v[222:225], v[64:67]
	v_mfma_f32_16x16x32_bf16 v[116:119], v[186:189], v[202:205], v[116:119]
	v_mfma_f32_16x16x32_bf16 v[112:115], v[194:197], v[202:205], v[112:115]
	v_mfma_f32_16x16x32_bf16 v[100:103], v[186:189], v[210:213], v[100:103]
	v_mfma_f32_16x16x32_bf16 v[92:95], v[194:197], v[210:213], v[92:95]
	v_mfma_f32_16x16x32_bf16 v[84:87], v[186:189], v[218:221], v[84:87]
	v_mfma_f32_16x16x32_bf16 v[76:79], v[194:197], v[218:221], v[76:79]
	v_mfma_f32_16x16x32_bf16 v[68:71], v[186:189], v[226:229], v[68:71]
	v_mfma_f32_16x16x32_bf16 v[64:67], v[194:197], v[226:229], v[64:67]
	s_barrier
; #define PG8_STAGE(bufoff, gbase, voff) do { _Pragma("unroll") for (int _i = 0; _i < 2; ++_i) \
;         __builtin_amdgcn_global_load_lds((const unsigned*)((const char*)(gbase) + (voff)[_i]), (PG8_LAS unsigned*)(lds + (bufoff) + ldsw + _i * 8192), 16, 0, 0); } while (0)
; #define PG8_LDA(dst, b, h) do { _Pragma("unroll") for (int m = 0; m < 4; ++m) _Pragma("unroll") for (int k = 0; k < 2; ++k) dst[m][k] = *(const PG8_LAS bf16x8*)(lds + PG8_SA(b, h) + aoff + m * 2048 + k * 1024); } while (0)
; #define PG8_MMA(ai, bj, At, Bt) do { __builtin_amdgcn_s_setprio(1); _Pragma("unroll") for (int m = 0; m < 4; ++m) _Pragma("unroll") for (int n = 0; n < 2; ++n) _Pragma("unroll") for (int k = 0; k < 2; ++k) \
;         acc[ai][bj][m][n] = __builtin_amdgcn_mfma_f32_16x16x32_bf16(Bt[n][k], At[m][k], acc[ai][bj][m][n], 0, 0, 0); __builtin_amdgcn_s_setprio(0); } while (0)
; #define PG8_WAIT_V(n) asm volatile("s_waitcnt vmcnt(" #n ")" ::: "memory")
; #define PG8_WAIT_L(n) asm volatile("s_waitcnt lgkmcnt(" #n ")" ::: "memory")
; #define PG8_BAR __builtin_amdgcn_s_barrier()
; #define PG8_SCHED __builtin_amdgcn_sched_barrier(0)
; template <class Epi, class Sched, bool ALIGN_EPI = false, bool SP2 = false>
; __device__ __forceinline__ void gemm_phase(PG8_LAS unsigned char* lds, const Gemm g, const Sched& S, const Epi& E) {
;     ...
;             PG8_WAIT_V(8); PG8_WAIT_L(0); PG8_BAR; PG8_MMA(0, 0, At, B0); PG8_MMA(0, 1, At, B1); PG8_BAR; PG8_SCHED;
;             PG8_LDA(At, 1, 1); PG8_STAGE(PG8_SB(1, 0), b3, voffB); PG8_STAGE(PG8_SB(1, 1), b3 + hstep, voffB); PG8_STAGE(PG8_SA(1, 0), a3, voffA);
;             PG8_WAIT_V(8); PG8_WAIT_L(0); PG8_BAR; PG8_MMA(1, 0, At, B0); PG8_MMA(1, 1, At, B1); PG8_BAR; PG8_SCHED;
	s_add_i32 s46, s63, s34
	v_lshl_add_u64 v[154:155], v[154:155], 0, s[96:97]
	s_mov_b32 m0, s46
	ds_read_b128 v[198:201], v149 offset:49152
	ds_read_b128 v[202:205], v149 offset:50176
	ds_read_b128 v[206:209], v149 offset:51200
	ds_read_b128 v[210:213], v149 offset:52224
	ds_read_b128 v[214:217], v149 offset:53248
	ds_read_b128 v[218:221], v149 offset:54272
	ds_read_b128 v[222:225], v149 offset:55296
	ds_read_b128 v[226:229], v149 offset:56320
	global_load_lds_dwordx4 v[154:155], off
	s_add_i32 m0, s46, 0x2000
	s_add_u32 s44, s44, 0x40080
	v_lshl_add_u64 v[154:155], v[236:237], 0, s[96:97]
	s_addc_u32 s45, s45, 0
	s_add_i32 s46, s64, s34
	global_load_lds_dwordx4 v[154:155], off
	v_lshl_add_u64 v[154:155], s[44:45], 0, v[132:133]
	s_mov_b32 m0, s46
	s_nop 0
	global_load_lds_dwordx4 v[154:155], off
	v_lshl_add_u64 v[154:155], s[44:45], 0, v[128:129]
	s_add_i32 m0, s46, 0x2000
	s_nop 0
	global_load_lds_dwordx4 v[154:155], off
	v_lshl_add_u64 v[154:155], v[238:239], 0, s[96:97]
	s_mov_b32 m0, s58
	s_nop 0
	global_load_lds_dwordx4 v[154:155], off
	v_lshl_add_u64 v[154:155], v[240:241], 0, s[96:97]
	s_mov_b32 m0, s59
	s_nop 0
	global_load_lds_dwordx4 v[154:155], off
	s_waitcnt vmcnt(8)
	s_waitcnt lgkmcnt(0)
	s_barrier
	s_waitcnt lgkmcnt(0)
	v_mfma_f32_16x16x32_bf16 v[60:63], v[150:153], v[198:201], v[60:63]
	v_mfma_f32_16x16x32_bf16 v[56:59], v[174:177], v[198:201], v[56:59]
	v_mfma_f32_16x16x32_bf16 v[44:47], v[150:153], v[206:209], v[44:47]
	v_mfma_f32_16x16x32_bf16 v[40:43], v[174:177], v[206:209], v[40:43]
	v_mfma_f32_16x16x32_bf16 v[32:35], v[150:153], v[214:217], v[32:35]
	v_mfma_f32_16x16x32_bf16 v[24:27], v[174:177], v[214:217], v[24:27]
	v_mfma_f32_16x16x32_bf16 v[16:19], v[150:153], v[222:225], v[16:19]
	v_mfma_f32_16x16x32_bf16 v[8:11], v[174:177], v[222:225], v[8:11]
	v_mfma_f32_16x16x32_bf16 v[60:63], v[170:173], v[202:205], v[60:63]
	v_mfma_f32_16x16x32_bf16 v[56:59], v[178:181], v[202:205], v[56:59]
	v_mfma_f32_16x16x32_bf16 v[44:47], v[170:173], v[210:213], v[44:47]
	v_mfma_f32_16x16x32_bf16 v[40:43], v[178:181], v[210:213], v[40:43]
	v_mfma_f32_16x16x32_bf16 v[32:35], v[170:173], v[218:221], v[32:35]
	v_mfma_f32_16x16x32_bf16 v[24:27], v[178:181], v[218:221], v[24:27]
	v_mfma_f32_16x16x32_bf16 v[16:19], v[170:173], v[226:229], v[16:19]
	v_mfma_f32_16x16x32_bf16 v[8:11], v[178:181], v[226:229], v[8:11]
	v_mfma_f32_16x16x32_bf16 v[52:55], v[182:185], v[198:201], v[52:55]
	v_mfma_f32_16x16x32_bf16 v[48:51], v[190:193], v[198:201], v[48:51]
	v_mfma_f32_16x16x32_bf16 v[36:39], v[182:185], v[206:209], v[36:39]
	v_mfma_f32_16x16x32_bf16 v[28:31], v[190:193], v[206:209], v[28:31]
	v_mfma_f32_16x16x32_bf16 v[20:23], v[182:185], v[214:217], v[20:23]
	v_mfma_f32_16x16x32_bf16 v[12:15], v[190:193], v[214:217], v[12:15]
	v_mfma_f32_16x16x32_bf16 v[4:7], v[182:185], v[222:225], v[4:7]
	v_mfma_f32_16x16x32_bf16 v[0:3], v[190:193], v[222:225], v[0:3]
	v_mfma_f32_16x16x32_bf16 v[52:55], v[186:189], v[202:205], v[52:55]
	v_mfma_f32_16x16x32_bf16 v[48:51], v[194:197], v[202:205], v[48:51]
	v_mfma_f32_16x16x32_bf16 v[36:39], v[186:189], v[210:213], v[36:39]
	v_mfma_f32_16x16x32_bf16 v[28:31], v[194:197], v[210:213], v[28:31]
	v_mfma_f32_16x16x32_bf16 v[20:23], v[186:189], v[218:221], v[20:23]
	v_mfma_f32_16x16x32_bf16 v[12:15], v[194:197], v[218:221], v[12:15]
	v_mfma_f32_16x16x32_bf16 v[4:7], v[186:189], v[226:229], v[4:7]
	v_mfma_f32_16x16x32_bf16 v[0:3], v[194:197], v[226:229], v[0:3]
	s_barrier
	s_add_i32 s62, s62, 2
	s_add_u32 s42, s42, 0x100
	s_addc_u32 s43, s43, 0
	s_add_u32 s60, s60, 0x100
	s_addc_u32 s61, s61, 0
	s_cmp_gt_u32 s62, 13
	s_cbranch_scc0 .LBB0_237
	s_and_b64 vcc, exec, s[8:9]
	s_cbranch_vccz .LBB0_240
	s_barrier

; #define PG8_STAGE(bufoff, gbase, voff) do { _Pragma("unroll") for (int _i = 0; _i < 2; ++_i) \
;         __builtin_amdgcn_global_load_lds((const unsigned*)((const char*)(gbase) + (voff)[_i]), (PG8_LAS unsigned*)(lds + (bufoff) + ldsw + _i * 8192), 16, 0, 0); } while (0)
; #define PG8_LDA(dst, b, h) do { _Pragma("unroll") for (int m = 0; m < 4; ++m) _Pragma("unroll") for (int k = 0; k < 2; ++k) dst[m][k] = *(const PG8_LAS bf16x8*)(lds + PG8_SA(b, h) + aoff + m * 2048 + k * 1024); } while (0)
; #define PG8_LDB(dst, b, h) do { _Pragma("unroll") for (int n = 0; n < 2; ++n) _Pragma("unroll") for (int k = 0; k < 2; ++k) dst[n][k] = *(const PG8_LAS bf16x8*)(lds + PG8_SB(b, h) + boff + n * 2048 + k * 1024); } while (0)
; #define PG8_MMA(ai, bj, At, Bt) do { __builtin_amdgcn_s_setprio(1); _Pragma("unroll") for (int m = 0; m < 4; ++m) _Pragma("unroll") for (int n = 0; n < 2; ++n) _Pragma("unroll") for (int k = 0; k < 2; ++k) \
;         acc[ai][bj][m][n] = __builtin_amdgcn_mfma_f32_16x16x32_bf16(Bt[n][k], At[m][k], acc[ai][bj][m][n], 0, 0, 0); __builtin_amdgcn_s_setprio(0); } while (0)
; #define PG8_WAIT_V(n) asm volatile("s_waitcnt vmcnt(" #n ")" ::: "memory")
; #define PG8_WAIT_L(n) asm volatile("s_waitcnt lgkmcnt(" #n ")" ::: "memory")
; #define PG8_BAR __builtin_amdgcn_s_barrier()
; #define PG8_SCHED __builtin_amdgcn_sched_barrier(0)
; template <class Epi, class Sched, bool ALIGN_EPI = false, bool SP2 = false>
; __device__ __forceinline__ void gemm_phase(PG8_LAS unsigned char* lds, const Gemm g, const Sched& S, const Epi& E) {
;     ...
;             if constexpr (SP2) {
;             PG8_LDB(B0, 0, 0); PG8_LDB(B1, 0, 1); PG8_SCHED; PG8_LDA(At, 0, 0); PG8_STAGE(PG8_SA(1, 1), a1 + hstep, voffA);
;             PG8_WAIT_V(8); PG8_WAIT_L(0); PG8_BAR; PG8_MMA(0, 0, At, B0); PG8_MMA(0, 1, At, B1); PG8_BAR; PG8_SCHED;
;             PG8_LDA(At, 0, 1); PG8_STAGE(PG8_SB(0, 0), b2, voffB); PG8_STAGE(PG8_SB(0, 1), b2 + hstep, voffB); PG8_STAGE(PG8_SA(0, 0), a2, voffA);
;             PG8_WAIT_V(8); PG8_WAIT_L(0); PG8_BAR; PG8_MMA(1, 0, At, B0); PG8_MMA(1, 1, At, B1); PG8_BAR; PG8_SCHED;
.LBB0_264:
	s_add_u32 s12, s10, 0x100
	s_addc_u32 s13, s11, 0
	s_add_i32 s34, 0, 0x10000
	s_cmp_eq_u32 s31, 40
	s_cselect_b32 s17, s7, s13
	s_cselect_b32 s16, s6, s12
	s_cselect_b32 s15, s9, s30
	s_cselect_b32 s14, s8, s29
	s_add_i32 s35, 0, 0x14000
	v_add_u32_e32 v132, s34, v169
	v_add_u32_e32 v180, s35, v169
	ds_read_b128 v[104:107], v132
	ds_read_b128 v[120:123], v132 offset:1024
	ds_read_b128 v[128:131], v132 offset:2048
	ds_read_b128 v[132:135], v132 offset:3072
	ds_read_b128 v[136:139], v180
	ds_read_b128 v[148:151], v180 offset:1024
	ds_read_b128 v[152:155], v180 offset:2048
	ds_read_b128 v[180:183], v180 offset:3072
	v_lshl_add_u64 v[216:217], s[10:11], 0, v[176:177]
	s_add_i32 m0, s21, 0xc000
	ds_read_b128 v[184:187], v239
	ds_read_b128 v[188:191], v239 offset:1024
	ds_read_b128 v[192:195], v239 offset:2048
	ds_read_b128 v[196:199], v239 offset:3072
	ds_read_b128 v[200:203], v239 offset:4096
	ds_read_b128 v[204:207], v239 offset:5120
	ds_read_b128 v[208:211], v239 offset:6144
	ds_read_b128 v[212:215], v239 offset:7168
	global_load_lds_dwordx4 v[216:217], off
	v_lshl_add_u64 v[216:217], s[10:11], 0, v[178:179]
	s_add_i32 m0, s21, 0xe000
	s_nop 0
	global_load_lds_dwordx4 v[216:217], off
	s_waitcnt vmcnt(8)
	s_waitcnt lgkmcnt(0)
	s_barrier
	s_waitcnt lgkmcnt(0)
	v_mfma_f32_16x16x32_bf16 v[144:147], v[104:107], v[184:187], v[144:147]
	v_mfma_f32_16x16x32_bf16 v[140:143], v[128:131], v[184:187], v[140:143]
	v_mfma_f32_16x16x32_bf16 v[112:115], v[104:107], v[192:195], v[112:115]
	v_mfma_f32_16x16x32_bf16 v[108:111], v[128:131], v[192:195], v[108:111]
	v_mfma_f32_16x16x32_bf16 v[92:95], v[104:107], v[200:203], v[92:95]
	v_mfma_f32_16x16x32_bf16 v[88:91], v[128:131], v[200:203], v[88:91]
	v_mfma_f32_16x16x32_bf16 v[76:79], v[104:107], v[208:211], v[76:79]
	v_mfma_f32_16x16x32_bf16 v[72:75], v[128:131], v[208:211], v[72:75]
	v_mfma_f32_16x16x32_bf16 v[144:147], v[120:123], v[188:191], v[144:147]
	v_mfma_f32_16x16x32_bf16 v[140:143], v[132:135], v[188:191], v[140:143]
	v_mfma_f32_16x16x32_bf16 v[112:115], v[120:123], v[196:199], v[112:115]
	v_mfma_f32_16x16x32_bf16 v[108:111], v[132:135], v[196:199], v[108:111]
	v_mfma_f32_16x16x32_bf16 v[92:95], v[120:123], v[204:207], v[92:95]
	v_mfma_f32_16x16x32_bf16 v[88:91], v[132:135], v[204:207], v[88:91]
	v_mfma_f32_16x16x32_bf16 v[76:79], v[120:123], v[212:215], v[76:79]
	v_mfma_f32_16x16x32_bf16 v[72:75], v[132:135], v[212:215], v[72:75]
	v_mfma_f32_16x16x32_bf16 v[124:127], v[136:139], v[184:187], v[124:127]
	v_mfma_f32_16x16x32_bf16 v[116:119], v[152:155], v[184:187], v[116:119]
	v_mfma_f32_16x16x32_bf16 v[100:103], v[136:139], v[192:195], v[100:103]
	v_mfma_f32_16x16x32_bf16 v[96:99], v[152:155], v[192:195], v[96:99]
	v_mfma_f32_16x16x32_bf16 v[84:87], v[136:139], v[200:203], v[84:87]
	v_mfma_f32_16x16x32_bf16 v[80:83], v[152:155], v[200:203], v[80:83]
	v_mfma_f32_16x16x32_bf16 v[68:71], v[136:139], v[208:211], v[68:71]
	v_mfma_f32_16x16x32_bf16 v[64:67], v[152:155], v[208:211], v[64:67]
	v_mfma_f32_16x16x32_bf16 v[124:127], v[148:151], v[188:191], v[124:127]
	v_mfma_f32_16x16x32_bf16 v[116:119], v[180:183], v[188:191], v[116:119]
	v_mfma_f32_16x16x32_bf16 v[100:103], v[148:151], v[196:199], v[100:103]
	v_mfma_f32_16x16x32_bf16 v[96:99], v[180:183], v[196:199], v[96:99]
	v_mfma_f32_16x16x32_bf16 v[84:87], v[148:151], v[204:207], v[84:87]
	v_mfma_f32_16x16x32_bf16 v[80:83], v[180:183], v[204:207], v[80:83]
	v_mfma_f32_16x16x32_bf16 v[68:71], v[148:151], v[212:215], v[68:71]
	v_mfma_f32_16x16x32_bf16 v[64:67], v[180:183], v[212:215], v[64:67]
	s_barrier
	s_add_i32 s10, s34, s20
	v_lshl_add_u64 v[216:217], s[14:15], 0, v[156:157]
	s_mov_b32 m0, s10
	ds_read_b128 v[184:187], v239 offset:16384
	ds_read_b128 v[188:191], v239 offset:17408
	ds_read_b128 v[192:195], v239 offset:18432
	ds_read_b128 v[196:199], v239 offset:19456
	ds_read_b128 v[200:203], v239 offset:20480
	ds_read_b128 v[204:207], v239 offset:21504
	ds_read_b128 v[208:211], v239 offset:22528
	ds_read_b128 v[212:215], v239 offset:23552
	global_load_lds_dwordx4 v[216:217], off
	s_add_i32 m0, s10, 0x2000
	s_add_u32 s10, s14, 0xb0000
	v_lshl_add_u64 v[218:219], s[14:15], 0, v[170:171]
	s_addc_u32 s11, s15, 0
	s_add_i32 s34, s35, s20
	global_load_lds_dwordx4 v[218:219], off
	v_lshl_add_u64 v[220:221], s[10:11], 0, v[156:157]
	s_mov_b32 m0, s34
	v_lshl_add_u64 v[222:223], s[16:17], 0, v[172:173]
	global_load_lds_dwordx4 v[220:221], off
	v_lshl_add_u64 v[220:221], s[10:11], 0, v[170:171]
	s_add_i32 m0, s34, 0x2000
	s_nop 0
	global_load_lds_dwordx4 v[220:221], off
	v_lshl_add_u64 v[220:221], s[16:17], 0, v[174:175]
	s_mov_b32 m0, s21
	s_nop 0
	global_load_lds_dwordx4 v[220:221], off
	s_mov_b32 m0, s27
	s_nop 0
	global_load_lds_dwordx4 v[222:223], off
	s_waitcnt vmcnt(8)
	s_waitcnt lgkmcnt(0)
	s_barrier
; #define PG8_STAGE(bufoff, gbase, voff) do { _Pragma("unroll") for (int _i = 0; _i < 2; ++_i) \
;         __builtin_amdgcn_global_load_lds((const unsigned*)((const char*)(gbase) + (voff)[_i]), (PG8_LAS unsigned*)(lds + (bufoff) + ldsw + _i * 8192), 16, 0, 0); } while (0)
; #define PG8_LDA(dst, b, h) do { _Pragma("unroll") for (int m = 0; m < 4; ++m) _Pragma("unroll") for (int k = 0; k < 2; ++k) dst[m][k] = *(const PG8_LAS bf16x8*)(lds + PG8_SA(b, h) + aoff + m * 2048 + k * 1024); } while (0)
; #define PG8_LDB(dst, b, h) do { _Pragma("unroll") for (int n = 0; n < 2; ++n) _Pragma("unroll") for (int k = 0; k < 2; ++k) dst[n][k] = *(const PG8_LAS bf16x8*)(lds + PG8_SB(b, h) + boff + n * 2048 + k * 1024); } while (0)
; #define PG8_MMA(ai, bj, At, Bt) do { __builtin_amdgcn_s_setprio(1); _Pragma("unroll") for (int m = 0; m < 4; ++m) _Pragma("unroll") for (int n = 0; n < 2; ++n) _Pragma("unroll") for (int k = 0; k < 2; ++k) \
;         acc[ai][bj][m][n] = __builtin_amdgcn_mfma_f32_16x16x32_bf16(Bt[n][k], At[m][k], acc[ai][bj][m][n], 0, 0, 0); __builtin_amdgcn_s_setprio(0); } while (0)
; #define PG8_WAIT_V(n) asm volatile("s_waitcnt vmcnt(" #n ")" ::: "memory")
; #define PG8_WAIT_L(n) asm volatile("s_waitcnt lgkmcnt(" #n ")" ::: "memory")
; #define PG8_BAR __builtin_amdgcn_s_barrier()
; #define PG8_SCHED __builtin_amdgcn_sched_barrier(0)
; template <class Epi, class Sched, bool ALIGN_EPI = false, bool SP2 = false>
; __device__ __forceinline__ void gemm_phase(PG8_LAS unsigned char* lds, const Gemm g, const Sched& S, const Epi& E) {
;     ...
;             PG8_WAIT_V(8); PG8_WAIT_L(0); PG8_BAR; PG8_MMA(0, 0, At, B0); PG8_MMA(0, 1, At, B1); PG8_BAR; PG8_SCHED;
;             PG8_LDA(At, 0, 1); PG8_STAGE(PG8_SB(0, 0), b2, voffB); PG8_STAGE(PG8_SB(0, 1), b2 + hstep, voffB); PG8_STAGE(PG8_SA(0, 0), a2, voffA);
;             PG8_WAIT_V(8); PG8_WAIT_L(0); PG8_BAR; PG8_MMA(1, 0, At, B0); PG8_MMA(1, 1, At, B1); PG8_BAR; PG8_SCHED;
;             PG8_LDB(B0, 1, 0); PG8_LDB(B1, 1, 1); PG8_SCHED; PG8_LDA(At, 1, 0); PG8_STAGE(PG8_SA(0, 1), a2 + hstep, voffA);
;             PG8_WAIT_V(8); PG8_WAIT_L(0); PG8_BAR; PG8_MMA(0, 0, At, B0); PG8_MMA(0, 1, At, B1); PG8_BAR; PG8_SCHED;
	s_waitcnt lgkmcnt(0)
	v_mfma_f32_16x16x32_bf16 v[60:63], v[104:107], v[184:187], v[60:63]
	v_mfma_f32_16x16x32_bf16 v[56:59], v[128:131], v[184:187], v[56:59]
	v_mfma_f32_16x16x32_bf16 v[44:47], v[104:107], v[192:195], v[44:47]
	v_mfma_f32_16x16x32_bf16 v[40:43], v[128:131], v[192:195], v[40:43]
	v_mfma_f32_16x16x32_bf16 v[28:31], v[104:107], v[200:203], v[28:31]
	v_mfma_f32_16x16x32_bf16 v[24:27], v[128:131], v[200:203], v[24:27]
	v_mfma_f32_16x16x32_bf16 v[12:15], v[104:107], v[208:211], v[12:15]
	v_mfma_f32_16x16x32_bf16 v[8:11], v[128:131], v[208:211], v[8:11]
	v_mfma_f32_16x16x32_bf16 v[60:63], v[120:123], v[188:191], v[60:63]
	v_mfma_f32_16x16x32_bf16 v[56:59], v[132:135], v[188:191], v[56:59]
	v_mfma_f32_16x16x32_bf16 v[44:47], v[120:123], v[196:199], v[44:47]
	v_mfma_f32_16x16x32_bf16 v[40:43], v[132:135], v[196:199], v[40:43]
	v_mfma_f32_16x16x32_bf16 v[28:31], v[120:123], v[204:207], v[28:31]
	v_mfma_f32_16x16x32_bf16 v[24:27], v[132:135], v[204:207], v[24:27]
	v_mfma_f32_16x16x32_bf16 v[12:15], v[120:123], v[212:215], v[12:15]
	v_mfma_f32_16x16x32_bf16 v[8:11], v[132:135], v[212:215], v[8:11]
	v_mfma_f32_16x16x32_bf16 v[52:55], v[136:139], v[184:187], v[52:55]
	v_mfma_f32_16x16x32_bf16 v[48:51], v[152:155], v[184:187], v[48:51]
	v_mfma_f32_16x16x32_bf16 v[36:39], v[136:139], v[192:195], v[36:39]
	v_mfma_f32_16x16x32_bf16 v[32:35], v[152:155], v[192:195], v[32:35]
	v_mfma_f32_16x16x32_bf16 v[20:23], v[136:139], v[200:203], v[20:23]
	v_mfma_f32_16x16x32_bf16 v[16:19], v[152:155], v[200:203], v[16:19]
	v_mfma_f32_16x16x32_bf16 v[4:7], v[136:139], v[208:211], v[4:7]
	v_mfma_f32_16x16x32_bf16 v[0:3], v[152:155], v[208:211], v[0:3]
	v_mfma_f32_16x16x32_bf16 v[52:55], v[148:151], v[188:191], v[52:55]
	v_mfma_f32_16x16x32_bf16 v[48:51], v[180:183], v[188:191], v[48:51]
	v_mfma_f32_16x16x32_bf16 v[36:39], v[148:151], v[196:199], v[36:39]
	v_mfma_f32_16x16x32_bf16 v[32:35], v[180:183], v[196:199], v[32:35]
	v_mfma_f32_16x16x32_bf16 v[20:23], v[148:151], v[204:207], v[20:23]
	v_mfma_f32_16x16x32_bf16 v[16:19], v[180:183], v[204:207], v[16:19]
	v_mfma_f32_16x16x32_bf16 v[4:7], v[148:151], v[212:215], v[4:7]
	v_mfma_f32_16x16x32_bf16 v[0:3], v[180:183], v[212:215], v[0:3]
	s_barrier
	s_add_i32 s34, 0, 0x18000
	s_add_i32 s35, 0, 0x1c000
	v_add_u32_e32 v132, s34, v169
	v_add_u32_e32 v180, s35, v169
	ds_read_b128 v[104:107], v132
	ds_read_b128 v[120:123], v132 offset:1024
	ds_read_b128 v[128:131], v132 offset:2048
	ds_read_b128 v[132:135], v132 offset:3072
	ds_read_b128 v[136:139], v180
	ds_read_b128 v[148:151], v180 offset:1024
	ds_read_b128 v[152:155], v180 offset:2048
	ds_read_b128 v[180:183], v180 offset:3072
	s_add_u32 s10, s16, 0xb0000
	s_addc_u32 s11, s17, 0
	s_mov_b32 m0, s54
	v_lshl_add_u64 v[224:225], s[10:11], 0, v[174:175]
	ds_read_b128 v[184:187], v239 offset:32768
	ds_read_b128 v[188:191], v239 offset:33792
	ds_read_b128 v[192:195], v239 offset:34816
	ds_read_b128 v[196:199], v239 offset:35840
	ds_read_b128 v[200:203], v239 offset:36864
	ds_read_b128 v[204:207], v239 offset:37888
	ds_read_b128 v[208:211], v239 offset:38912
	ds_read_b128 v[212:215], v239 offset:39936
	global_load_lds_dwordx4 v[224:225], off
	v_lshl_add_u64 v[224:225], s[10:11], 0, v[172:173]
	s_mov_b32 m0, s55
	s_nop 0
	global_load_lds_dwordx4 v[224:225], off
	s_waitcnt vmcnt(8)
	s_waitcnt lgkmcnt(0)
	s_barrier
	s_waitcnt lgkmcnt(0)
	v_mfma_f32_16x16x32_bf16 v[144:147], v[104:107], v[184:187], v[144:147]
	v_mfma_f32_16x16x32_bf16 v[140:143], v[128:131], v[184:187], v[140:143]
	v_mfma_f32_16x16x32_bf16 v[112:115], v[104:107], v[192:195], v[112:115]
	v_mfma_f32_16x16x32_bf16 v[108:111], v[128:131], v[192:195], v[108:111]
	v_mfma_f32_16x16x32_bf16 v[92:95], v[104:107], v[200:203], v[92:95]
	v_mfma_f32_16x16x32_bf16 v[88:91], v[128:131], v[200:203], v[88:91]
	v_mfma_f32_16x16x32_bf16 v[76:79], v[104:107], v[208:211], v[76:79]
	v_mfma_f32_16x16x32_bf16 v[72:75], v[128:131], v[208:211], v[72:75]
	v_mfma_f32_16x16x32_bf16 v[144:147], v[120:123], v[188:191], v[144:147]
	v_mfma_f32_16x16x32_bf16 v[140:143], v[132:135], v[188:191], v[140:143]
	v_mfma_f32_16x16x32_bf16 v[112:115], v[120:123], v[196:199], v[112:115]
	v_mfma_f32_16x16x32_bf16 v[108:111], v[132:135], v[196:199], v[108:111]
	v_mfma_f32_16x16x32_bf16 v[92:95], v[120:123], v[204:207], v[92:95]
	v_mfma_f32_16x16x32_bf16 v[88:91], v[132:135], v[204:207], v[88:91]
	v_mfma_f32_16x16x32_bf16 v[76:79], v[120:123], v[212:215], v[76:79]
	v_mfma_f32_16x16x32_bf16 v[72:75], v[132:135], v[212:215], v[72:75]
	v_mfma_f32_16x16x32_bf16 v[124:127], v[136:139], v[184:187], v[124:127]
	v_mfma_f32_16x16x32_bf16 v[116:119], v[152:155], v[184:187], v[116:119]
	v_mfma_f32_16x16x32_bf16 v[100:103], v[136:139], v[192:195], v[100:103]
	v_mfma_f32_16x16x32_bf16 v[96:99], v[152:155], v[192:195], v[96:99]
	v_mfma_f32_16x16x32_bf16 v[84:87], v[136:139], v[200:203], v[84:87]
	v_mfma_f32_16x16x32_bf16 v[80:83], v[152:155], v[200:203], v[80:83]
	v_mfma_f32_16x16x32_bf16 v[68:71], v[136:139], v[208:211], v[68:71]
	v_mfma_f32_16x16x32_bf16 v[64:67], v[152:155], v[208:211], v[64:67]
	v_mfma_f32_16x16x32_bf16 v[124:127], v[148:151], v[188:191], v[124:127]
	v_mfma_f32_16x16x32_bf16 v[116:119], v[180:183], v[188:191], v[116:119]
	v_mfma_f32_16x16x32_bf16 v[100:103], v[148:151], v[196:199], v[100:103]
	v_mfma_f32_16x16x32_bf16 v[96:99], v[180:183], v[196:199], v[96:99]
	v_mfma_f32_16x16x32_bf16 v[84:87], v[148:151], v[204:207], v[84:87]
	v_mfma_f32_16x16x32_bf16 v[80:83], v[180:183], v[204:207], v[80:83]
	v_mfma_f32_16x16x32_bf16 v[68:71], v[148:151], v[212:215], v[68:71]
	v_mfma_f32_16x16x32_bf16 v[64:67], v[180:183], v[212:215], v[64:67]
	s_barrier
; #define PG8_STAGE(bufoff, gbase, voff) do { _Pragma("unroll") for (int _i = 0; _i < 2; ++_i) \
;         __builtin_amdgcn_global_load_lds((const unsigned*)((const char*)(gbase) + (voff)[_i]), (PG8_LAS unsigned*)(lds + (bufoff) + ldsw + _i * 8192), 16, 0, 0); } while (0)
; #define PG8_LDA(dst, b, h) do { _Pragma("unroll") for (int m = 0; m < 4; ++m) _Pragma("unroll") for (int k = 0; k < 2; ++k) dst[m][k] = *(const PG8_LAS bf16x8*)(lds + PG8_SA(b, h) + aoff + m * 2048 + k * 1024); } while (0)
; #define PG8_MMA(ai, bj, At, Bt) do { __builtin_amdgcn_s_setprio(1); _Pragma("unroll") for (int m = 0; m < 4; ++m) _Pragma("unroll") for (int n = 0; n < 2; ++n) _Pragma("unroll") for (int k = 0; k < 2; ++k) \
;         acc[ai][bj][m][n] = __builtin_amdgcn_mfma_f32_16x16x32_bf16(Bt[n][k], At[m][k], acc[ai][bj][m][n], 0, 0, 0); __builtin_amdgcn_s_setprio(0); } while (0)
; #define PG8_WAIT_V(n) asm volatile("s_waitcnt vmcnt(" #n ")" ::: "memory")
; #define PG8_WAIT_L(n) asm volatile("s_waitcnt lgkmcnt(" #n ")" ::: "memory")
; #define PG8_BAR __builtin_amdgcn_s_barrier()
; #define PG8_SCHED __builtin_amdgcn_sched_barrier(0)
; template <class Epi, class Sched, bool ALIGN_EPI = false, bool SP2 = false>
; __device__ __forceinline__ void gemm_phase(PG8_LAS unsigned char* lds, const Gemm g, const Sched& S, const Epi& E) {
;     ...
;             PG8_WAIT_V(8); PG8_WAIT_L(0); PG8_BAR; PG8_MMA(0, 0, At, B0); PG8_MMA(0, 1, At, B1); PG8_BAR; PG8_SCHED;
;             PG8_LDA(At, 1, 1); PG8_STAGE(PG8_SB(1, 0), b3, voffB); PG8_STAGE(PG8_SB(1, 1), b3 + hstep, voffB); PG8_STAGE(PG8_SA(1, 0), a3, voffA);
;             PG8_WAIT_V(8); PG8_WAIT_L(0); PG8_BAR; PG8_MMA(1, 0, At, B0); PG8_MMA(1, 1, At, B1); PG8_BAR; PG8_SCHED;
	s_add_i32 s10, s34, s20
	v_lshl_add_u64 v[216:217], v[216:217], 0, s[96:97]
	s_mov_b32 m0, s10
	ds_read_b128 v[184:187], v239 offset:49152
	ds_read_b128 v[188:191], v239 offset:50176
	ds_read_b128 v[192:195], v239 offset:51200
	ds_read_b128 v[196:199], v239 offset:52224
	ds_read_b128 v[200:203], v239 offset:53248
	ds_read_b128 v[204:207], v239 offset:54272
	ds_read_b128 v[208:211], v239 offset:55296
	ds_read_b128 v[212:215], v239 offset:56320
	global_load_lds_dwordx4 v[216:217], off
	s_add_i32 m0, s10, 0x2000
	s_add_u32 s10, s14, 0xb0080
	v_lshl_add_u64 v[216:217], v[218:219], 0, s[96:97]
	s_addc_u32 s11, s15, 0
	s_add_i32 s14, s35, s20
	global_load_lds_dwordx4 v[216:217], off
	v_lshl_add_u64 v[216:217], s[10:11], 0, v[156:157]
	s_mov_b32 m0, s14
	s_nop 0
	global_load_lds_dwordx4 v[216:217], off
	v_lshl_add_u64 v[216:217], s[10:11], 0, v[170:171]
	s_add_i32 m0, s14, 0x2000
	s_nop 0
	global_load_lds_dwordx4 v[216:217], off
	v_lshl_add_u64 v[216:217], v[220:221], 0, s[96:97]
	s_mov_b32 m0, s57
	s_nop 0
	global_load_lds_dwordx4 v[216:217], off
	v_lshl_add_u64 v[216:217], v[222:223], 0, s[96:97]
	s_mov_b32 m0, s58
	s_nop 0
	global_load_lds_dwordx4 v[216:217], off
	s_waitcnt vmcnt(8)
	s_waitcnt lgkmcnt(0)
	s_barrier
	s_waitcnt lgkmcnt(0)
	v_mfma_f32_16x16x32_bf16 v[60:63], v[104:107], v[184:187], v[60:63]
	v_mfma_f32_16x16x32_bf16 v[56:59], v[128:131], v[184:187], v[56:59]
	v_mfma_f32_16x16x32_bf16 v[44:47], v[104:107], v[192:195], v[44:47]
	v_mfma_f32_16x16x32_bf16 v[40:43], v[128:131], v[192:195], v[40:43]
	v_mfma_f32_16x16x32_bf16 v[28:31], v[104:107], v[200:203], v[28:31]
	v_mfma_f32_16x16x32_bf16 v[24:27], v[128:131], v[200:203], v[24:27]
	v_mfma_f32_16x16x32_bf16 v[12:15], v[104:107], v[208:211], v[12:15]
	v_mfma_f32_16x16x32_bf16 v[8:11], v[128:131], v[208:211], v[8:11]
	v_mfma_f32_16x16x32_bf16 v[60:63], v[120:123], v[188:191], v[60:63]
	v_mfma_f32_16x16x32_bf16 v[56:59], v[132:135], v[188:191], v[56:59]
	v_mfma_f32_16x16x32_bf16 v[44:47], v[120:123], v[196:199], v[44:47]
	v_mfma_f32_16x16x32_bf16 v[40:43], v[132:135], v[196:199], v[40:43]
	v_mfma_f32_16x16x32_bf16 v[28:31], v[120:123], v[204:207], v[28:31]
	v_mfma_f32_16x16x32_bf16 v[24:27], v[132:135], v[204:207], v[24:27]
	v_mfma_f32_16x16x32_bf16 v[12:15], v[120:123], v[212:215], v[12:15]
	v_mfma_f32_16x16x32_bf16 v[8:11], v[132:135], v[212:215], v[8:11]
	v_mfma_f32_16x16x32_bf16 v[52:55], v[136:139], v[184:187], v[52:55]
	v_mfma_f32_16x16x32_bf16 v[48:51], v[152:155], v[184:187], v[48:51]
	v_mfma_f32_16x16x32_bf16 v[36:39], v[136:139], v[192:195], v[36:39]
	v_mfma_f32_16x16x32_bf16 v[32:35], v[152:155], v[192:195], v[32:35]
	v_mfma_f32_16x16x32_bf16 v[20:23], v[136:139], v[200:203], v[20:23]
	v_mfma_f32_16x16x32_bf16 v[16:19], v[152:155], v[200:203], v[16:19]
	v_mfma_f32_16x16x32_bf16 v[4:7], v[136:139], v[208:211], v[4:7]
	v_mfma_f32_16x16x32_bf16 v[0:3], v[152:155], v[208:211], v[0:3]
	v_mfma_f32_16x16x32_bf16 v[52:55], v[148:151], v[188:191], v[52:55]
	v_mfma_f32_16x16x32_bf16 v[48:51], v[180:183], v[188:191], v[48:51]
	v_mfma_f32_16x16x32_bf16 v[36:39], v[148:151], v[196:199], v[36:39]
	v_mfma_f32_16x16x32_bf16 v[32:35], v[180:183], v[196:199], v[32:35]
	v_mfma_f32_16x16x32_bf16 v[20:23], v[148:151], v[204:207], v[20:23]
	v_mfma_f32_16x16x32_bf16 v[16:19], v[180:183], v[204:207], v[16:19]
	v_mfma_f32_16x16x32_bf16 v[4:7], v[148:151], v[212:215], v[4:7]
	v_mfma_f32_16x16x32_bf16 v[0:3], v[180:183], v[212:215], v[0:3]
	s_barrier
	s_add_i32 s31, s31, 2
	s_add_u32 s29, s29, 0x100
	s_addc_u32 s30, s30, 0
	s_cmp_gt_u32 s31, 41
	s_mov_b64 s[10:11], s[12:13]
	s_cbranch_scc0 .LBB0_264
	s_and_b64 vcc, exec, s[52:53]
	s_cbranch_vccz .LBB0_267
	s_barrier

; #define PG8_STAGE(bufoff, gbase, voff) do { _Pragma("unroll") for (int _i = 0; _i < 2; ++_i) \
;         __builtin_amdgcn_global_load_lds((const unsigned*)((const char*)(gbase) + (voff)[_i]), (PG8_LAS unsigned*)(lds + (bufoff) + ldsw + _i * 8192), 16, 0, 0); } while (0)
; #define PG8_LDA(dst, b, h) do { _Pragma("unroll") for (int m = 0; m < 4; ++m) _Pragma("unroll") for (int k = 0; k < 2; ++k) dst[m][k] = *(const PG8_LAS bf16x8*)(lds + PG8_SA(b, h) + aoff + m * 2048 + k * 1024); } while (0)
; #define PG8_LDB(dst, b, h) do { _Pragma("unroll") for (int n = 0; n < 2; ++n) _Pragma("unroll") for (int k = 0; k < 2; ++k) dst[n][k] = *(const PG8_LAS bf16x8*)(lds + PG8_SB(b, h) + boff + n * 2048 + k * 1024); } while (0)
; #define PG8_MMA(ai, bj, At, Bt) do { __builtin_amdgcn_s_setprio(1); _Pragma("unroll") for (int m = 0; m < 4; ++m) _Pragma("unroll") for (int n = 0; n < 2; ++n) _Pragma("unroll") for (int k = 0; k < 2; ++k) \
;         acc[ai][bj][m][n] = __builtin_amdgcn_mfma_f32_16x16x32_bf16(Bt[n][k], At[m][k], acc[ai][bj][m][n], 0, 0, 0); __builtin_amdgcn_s_setprio(0); } while (0)
; #define PG8_WAIT_V(n) asm volatile("s_waitcnt vmcnt(" #n ")" ::: "memory")
; #define PG8_WAIT_L(n) asm volatile("s_waitcnt lgkmcnt(" #n ")" ::: "memory")
; #define PG8_BAR __builtin_amdgcn_s_barrier()
; #define PG8_SCHED __builtin_amdgcn_sched_barrier(0)
; template <class Epi, class Sched, bool ALIGN_EPI = false, bool SP2 = false>
; __device__ __forceinline__ void gemm_phase(PG8_LAS unsigned char* lds, const Gemm g, const Sched& S, const Epi& E) {
;     ...
;             if constexpr (SP2) {
;             PG8_LDB(B0, 0, 0); PG8_LDB(B1, 0, 1); PG8_SCHED; PG8_LDA(At, 0, 0); PG8_STAGE(PG8_SA(1, 1), a1 + hstep, voffA);
;             PG8_WAIT_V(8); PG8_WAIT_L(0); PG8_BAR; PG8_MMA(0, 0, At, B0); PG8_MMA(0, 1, At, B1); PG8_BAR; PG8_SCHED;
;             PG8_LDA(At, 0, 1); PG8_STAGE(PG8_SB(0, 0), b2, voffB); PG8_STAGE(PG8_SB(0, 1), b2 + hstep, voffB); PG8_STAGE(PG8_SA(0, 0), a2, voffA);
;             PG8_WAIT_V(8); PG8_WAIT_L(0); PG8_BAR; PG8_MMA(1, 0, At, B0); PG8_MMA(1, 1, At, B1); PG8_BAR; PG8_SCHED;
.LBB0_356:
	s_add_u32 s8, s6, 0xfffc0080
	s_addc_u32 s9, s7, -1
	s_add_i32 s54, 0, 0x10000
	s_cmp_eq_u32 s47, 12
	s_cselect_b32 s11, s29, s9
	s_cselect_b32 s10, s30, s8
	s_cselect_b32 s9, s31, s45
	s_cselect_b32 s8, s34, s35
	s_add_i32 s56, 0, 0x14000
	v_add_u32_e32 v132, s54, v169
	v_add_u32_e32 v180, s56, v169
	ds_read_b128 v[104:107], v132
	ds_read_b128 v[116:119], v132 offset:1024
	ds_read_b128 v[128:131], v132 offset:2048
	ds_read_b128 v[132:135], v132 offset:3072
	ds_read_b128 v[136:139], v180
	ds_read_b128 v[140:143], v180 offset:1024
	ds_read_b128 v[144:147], v180 offset:2048
	ds_read_b128 v[180:183], v180 offset:3072
	v_lshl_add_u64 v[216:217], s[6:7], 0, v[176:177]
	s_add_i32 m0, s15, 0xc000
	ds_read_b128 v[184:187], v239
	ds_read_b128 v[188:191], v239 offset:1024
	ds_read_b128 v[192:195], v239 offset:2048
	ds_read_b128 v[196:199], v239 offset:3072
	ds_read_b128 v[200:203], v239 offset:4096
	ds_read_b128 v[204:207], v239 offset:5120
	ds_read_b128 v[208:211], v239 offset:6144
	ds_read_b128 v[212:215], v239 offset:7168
	global_load_lds_dwordx4 v[216:217], off
	v_lshl_add_u64 v[216:217], s[6:7], 0, v[178:179]
	s_add_i32 m0, s15, 0xe000
	s_nop 0
	global_load_lds_dwordx4 v[216:217], off
	s_waitcnt vmcnt(8)
	s_waitcnt lgkmcnt(0)
	s_barrier
	s_waitcnt lgkmcnt(0)
	v_mfma_f32_16x16x32_bf16 v[152:155], v[104:107], v[184:187], v[152:155]
	v_mfma_f32_16x16x32_bf16 v[148:151], v[128:131], v[184:187], v[148:151]
	v_mfma_f32_16x16x32_bf16 v[112:115], v[104:107], v[192:195], v[112:115]
	v_mfma_f32_16x16x32_bf16 v[108:111], v[128:131], v[192:195], v[108:111]
	v_mfma_f32_16x16x32_bf16 v[92:95], v[104:107], v[200:203], v[92:95]
	v_mfma_f32_16x16x32_bf16 v[88:91], v[128:131], v[200:203], v[88:91]
	v_mfma_f32_16x16x32_bf16 v[76:79], v[104:107], v[208:211], v[76:79]
	v_mfma_f32_16x16x32_bf16 v[72:75], v[128:131], v[208:211], v[72:75]
	v_mfma_f32_16x16x32_bf16 v[152:155], v[116:119], v[188:191], v[152:155]
	v_mfma_f32_16x16x32_bf16 v[148:151], v[132:135], v[188:191], v[148:151]
	v_mfma_f32_16x16x32_bf16 v[112:115], v[116:119], v[196:199], v[112:115]
	v_mfma_f32_16x16x32_bf16 v[108:111], v[132:135], v[196:199], v[108:111]
	v_mfma_f32_16x16x32_bf16 v[92:95], v[116:119], v[204:207], v[92:95]
	v_mfma_f32_16x16x32_bf16 v[88:91], v[132:135], v[204:207], v[88:91]
	v_mfma_f32_16x16x32_bf16 v[76:79], v[116:119], v[212:215], v[76:79]
	v_mfma_f32_16x16x32_bf16 v[72:75], v[132:135], v[212:215], v[72:75]
	v_mfma_f32_16x16x32_bf16 v[124:127], v[136:139], v[184:187], v[124:127]
	v_mfma_f32_16x16x32_bf16 v[120:123], v[144:147], v[184:187], v[120:123]
	v_mfma_f32_16x16x32_bf16 v[100:103], v[136:139], v[192:195], v[100:103]
	v_mfma_f32_16x16x32_bf16 v[96:99], v[144:147], v[192:195], v[96:99]
	v_mfma_f32_16x16x32_bf16 v[84:87], v[136:139], v[200:203], v[84:87]
	v_mfma_f32_16x16x32_bf16 v[80:83], v[144:147], v[200:203], v[80:83]
	v_mfma_f32_16x16x32_bf16 v[68:71], v[136:139], v[208:211], v[68:71]
	v_mfma_f32_16x16x32_bf16 v[64:67], v[144:147], v[208:211], v[64:67]
	v_mfma_f32_16x16x32_bf16 v[124:127], v[140:143], v[188:191], v[124:127]
	v_mfma_f32_16x16x32_bf16 v[120:123], v[180:183], v[188:191], v[120:123]
	v_mfma_f32_16x16x32_bf16 v[100:103], v[140:143], v[196:199], v[100:103]
	v_mfma_f32_16x16x32_bf16 v[96:99], v[180:183], v[196:199], v[96:99]
	v_mfma_f32_16x16x32_bf16 v[84:87], v[140:143], v[204:207], v[84:87]
	v_mfma_f32_16x16x32_bf16 v[80:83], v[180:183], v[204:207], v[80:83]
	v_mfma_f32_16x16x32_bf16 v[68:71], v[140:143], v[212:215], v[68:71]
	v_mfma_f32_16x16x32_bf16 v[64:67], v[180:183], v[212:215], v[64:67]
	s_barrier
	s_add_i32 s54, s54, s14
	v_lshl_add_u64 v[216:217], s[8:9], 0, v[156:157]
	s_mov_b32 m0, s54
	ds_read_b128 v[184:187], v239 offset:16384
	ds_read_b128 v[188:191], v239 offset:17408
	ds_read_b128 v[192:195], v239 offset:18432
	ds_read_b128 v[196:199], v239 offset:19456
	ds_read_b128 v[200:203], v239 offset:20480
	ds_read_b128 v[204:207], v239 offset:21504
	ds_read_b128 v[208:211], v239 offset:22528
	ds_read_b128 v[212:215], v239 offset:23552
	global_load_lds_dwordx4 v[216:217], off
	s_add_i32 m0, s54, 0x2000
	s_add_u32 s54, s8, 0x40000
	v_lshl_add_u64 v[218:219], s[8:9], 0, v[170:171]
	s_addc_u32 s55, s9, 0
	s_add_i32 s56, s56, s14
	global_load_lds_dwordx4 v[218:219], off
	v_lshl_add_u64 v[220:221], s[54:55], 0, v[156:157]
	s_mov_b32 m0, s56
	v_lshl_add_u64 v[222:223], s[10:11], 0, v[172:173]
	global_load_lds_dwordx4 v[220:221], off
	v_lshl_add_u64 v[220:221], s[54:55], 0, v[170:171]
	s_add_i32 m0, s56, 0x2000
	s_nop 0
	global_load_lds_dwordx4 v[220:221], off
	v_lshl_add_u64 v[220:221], s[10:11], 0, v[174:175]
	s_mov_b32 m0, s15
	s_nop 0
	global_load_lds_dwordx4 v[220:221], off
	s_mov_b32 m0, s16
	s_nop 0
	global_load_lds_dwordx4 v[222:223], off
	s_waitcnt vmcnt(8)
	s_waitcnt lgkmcnt(0)
	s_barrier
; #define PG8_STAGE(bufoff, gbase, voff) do { _Pragma("unroll") for (int _i = 0; _i < 2; ++_i) \
;         __builtin_amdgcn_global_load_lds((const unsigned*)((const char*)(gbase) + (voff)[_i]), (PG8_LAS unsigned*)(lds + (bufoff) + ldsw + _i * 8192), 16, 0, 0); } while (0)
; #define PG8_LDA(dst, b, h) do { _Pragma("unroll") for (int m = 0; m < 4; ++m) _Pragma("unroll") for (int k = 0; k < 2; ++k) dst[m][k] = *(const PG8_LAS bf16x8*)(lds + PG8_SA(b, h) + aoff + m * 2048 + k * 1024); } while (0)
; #define PG8_LDB(dst, b, h) do { _Pragma("unroll") for (int n = 0; n < 2; ++n) _Pragma("unroll") for (int k = 0; k < 2; ++k) dst[n][k] = *(const PG8_LAS bf16x8*)(lds + PG8_SB(b, h) + boff + n * 2048 + k * 1024); } while (0)
; #define PG8_MMA(ai, bj, At, Bt) do { __builtin_amdgcn_s_setprio(1); _Pragma("unroll") for (int m = 0; m < 4; ++m) _Pragma("unroll") for (int n = 0; n < 2; ++n) _Pragma("unroll") for (int k = 0; k < 2; ++k) \
;         acc[ai][bj][m][n] = __builtin_amdgcn_mfma_f32_16x16x32_bf16(Bt[n][k], At[m][k], acc[ai][bj][m][n], 0, 0, 0); __builtin_amdgcn_s_setprio(0); } while (0)
; #define PG8_WAIT_V(n) asm volatile("s_waitcnt vmcnt(" #n ")" ::: "memory")
; #define PG8_WAIT_L(n) asm volatile("s_waitcnt lgkmcnt(" #n ")" ::: "memory")
; #define PG8_BAR __builtin_amdgcn_s_barrier()
; #define PG8_SCHED __builtin_amdgcn_sched_barrier(0)
; template <class Epi, class Sched, bool ALIGN_EPI = false, bool SP2 = false>
; __device__ __forceinline__ void gemm_phase(PG8_LAS unsigned char* lds, const Gemm g, const Sched& S, const Epi& E) {
;     ...
;             PG8_WAIT_V(8); PG8_WAIT_L(0); PG8_BAR; PG8_MMA(1, 0, At, B0); PG8_MMA(1, 1, At, B1); PG8_BAR; PG8_SCHED;
;             PG8_LDB(B0, 1, 0); PG8_LDB(B1, 1, 1); PG8_SCHED; PG8_LDA(At, 1, 0); PG8_STAGE(PG8_SA(0, 1), a2 + hstep, voffA);
;             PG8_WAIT_V(8); PG8_WAIT_L(0); PG8_BAR; PG8_MMA(0, 0, At, B0); PG8_MMA(0, 1, At, B1); PG8_BAR; PG8_SCHED;
	s_waitcnt lgkmcnt(0)
	v_mfma_f32_16x16x32_bf16 v[60:63], v[104:107], v[184:187], v[60:63]
	v_mfma_f32_16x16x32_bf16 v[56:59], v[128:131], v[184:187], v[56:59]
	v_mfma_f32_16x16x32_bf16 v[44:47], v[104:107], v[192:195], v[44:47]
	v_mfma_f32_16x16x32_bf16 v[40:43], v[128:131], v[192:195], v[40:43]
	v_mfma_f32_16x16x32_bf16 v[28:31], v[104:107], v[200:203], v[28:31]
	v_mfma_f32_16x16x32_bf16 v[24:27], v[128:131], v[200:203], v[24:27]
	v_mfma_f32_16x16x32_bf16 v[12:15], v[104:107], v[208:211], v[12:15]
	v_mfma_f32_16x16x32_bf16 v[8:11], v[128:131], v[208:211], v[8:11]
	v_mfma_f32_16x16x32_bf16 v[60:63], v[116:119], v[188:191], v[60:63]
	v_mfma_f32_16x16x32_bf16 v[56:59], v[132:135], v[188:191], v[56:59]
	v_mfma_f32_16x16x32_bf16 v[44:47], v[116:119], v[196:199], v[44:47]
	v_mfma_f32_16x16x32_bf16 v[40:43], v[132:135], v[196:199], v[40:43]
	v_mfma_f32_16x16x32_bf16 v[28:31], v[116:119], v[204:207], v[28:31]
	v_mfma_f32_16x16x32_bf16 v[24:27], v[132:135], v[204:207], v[24:27]
	v_mfma_f32_16x16x32_bf16 v[12:15], v[116:119], v[212:215], v[12:15]
	v_mfma_f32_16x16x32_bf16 v[8:11], v[132:135], v[212:215], v[8:11]
	v_mfma_f32_16x16x32_bf16 v[52:55], v[136:139], v[184:187], v[52:55]
	v_mfma_f32_16x16x32_bf16 v[48:51], v[144:147], v[184:187], v[48:51]
	v_mfma_f32_16x16x32_bf16 v[36:39], v[136:139], v[192:195], v[36:39]
	v_mfma_f32_16x16x32_bf16 v[32:35], v[144:147], v[192:195], v[32:35]
	v_mfma_f32_16x16x32_bf16 v[20:23], v[136:139], v[200:203], v[20:23]
	v_mfma_f32_16x16x32_bf16 v[16:19], v[144:147], v[200:203], v[16:19]
	v_mfma_f32_16x16x32_bf16 v[4:7], v[136:139], v[208:211], v[4:7]
	v_mfma_f32_16x16x32_bf16 v[0:3], v[144:147], v[208:211], v[0:3]
	v_mfma_f32_16x16x32_bf16 v[52:55], v[140:143], v[188:191], v[52:55]
	v_mfma_f32_16x16x32_bf16 v[48:51], v[180:183], v[188:191], v[48:51]
	v_mfma_f32_16x16x32_bf16 v[36:39], v[140:143], v[196:199], v[36:39]
	v_mfma_f32_16x16x32_bf16 v[32:35], v[180:183], v[196:199], v[32:35]
	v_mfma_f32_16x16x32_bf16 v[20:23], v[140:143], v[204:207], v[20:23]
	v_mfma_f32_16x16x32_bf16 v[16:19], v[180:183], v[204:207], v[16:19]
	v_mfma_f32_16x16x32_bf16 v[4:7], v[140:143], v[212:215], v[4:7]
	v_mfma_f32_16x16x32_bf16 v[0:3], v[180:183], v[212:215], v[0:3]
	s_barrier
	s_add_i32 s54, 0, 0x18000
	s_add_i32 s55, 0, 0x1c000
	v_add_u32_e32 v132, s54, v169
	v_add_u32_e32 v180, s55, v169
	ds_read_b128 v[104:107], v132
	ds_read_b128 v[116:119], v132 offset:1024
	ds_read_b128 v[128:131], v132 offset:2048
	ds_read_b128 v[132:135], v132 offset:3072
	ds_read_b128 v[136:139], v180
	ds_read_b128 v[140:143], v180 offset:1024
	ds_read_b128 v[144:147], v180 offset:2048
	ds_read_b128 v[180:183], v180 offset:3072
	s_add_u32 s10, s10, 0x40000
	s_addc_u32 s11, s11, 0
	s_mov_b32 m0, s17
	v_lshl_add_u64 v[224:225], s[10:11], 0, v[174:175]
	ds_read_b128 v[184:187], v239 offset:32768
	ds_read_b128 v[188:191], v239 offset:33792
	ds_read_b128 v[192:195], v239 offset:34816
	ds_read_b128 v[196:199], v239 offset:35840
	ds_read_b128 v[200:203], v239 offset:36864
	ds_read_b128 v[204:207], v239 offset:37888
	ds_read_b128 v[208:211], v239 offset:38912
	ds_read_b128 v[212:215], v239 offset:39936
	global_load_lds_dwordx4 v[224:225], off
	v_lshl_add_u64 v[224:225], s[10:11], 0, v[172:173]
	s_mov_b32 m0, s18
	s_nop 0
	global_load_lds_dwordx4 v[224:225], off
	s_waitcnt vmcnt(8)
	s_waitcnt lgkmcnt(0)
	s_barrier
	s_waitcnt lgkmcnt(0)
	v_mfma_f32_16x16x32_bf16 v[152:155], v[104:107], v[184:187], v[152:155]
	v_mfma_f32_16x16x32_bf16 v[148:151], v[128:131], v[184:187], v[148:151]
	v_mfma_f32_16x16x32_bf16 v[112:115], v[104:107], v[192:195], v[112:115]
	v_mfma_f32_16x16x32_bf16 v[108:111], v[128:131], v[192:195], v[108:111]
	v_mfma_f32_16x16x32_bf16 v[92:95], v[104:107], v[200:203], v[92:95]
	v_mfma_f32_16x16x32_bf16 v[88:91], v[128:131], v[200:203], v[88:91]
	v_mfma_f32_16x16x32_bf16 v[76:79], v[104:107], v[208:211], v[76:79]
	v_mfma_f32_16x16x32_bf16 v[72:75], v[128:131], v[208:211], v[72:75]
	v_mfma_f32_16x16x32_bf16 v[152:155], v[116:119], v[188:191], v[152:155]
	v_mfma_f32_16x16x32_bf16 v[148:151], v[132:135], v[188:191], v[148:151]
	v_mfma_f32_16x16x32_bf16 v[112:115], v[116:119], v[196:199], v[112:115]
	v_mfma_f32_16x16x32_bf16 v[108:111], v[132:135], v[196:199], v[108:111]
	v_mfma_f32_16x16x32_bf16 v[92:95], v[116:119], v[204:207], v[92:95]
	v_mfma_f32_16x16x32_bf16 v[88:91], v[132:135], v[204:207], v[88:91]
	v_mfma_f32_16x16x32_bf16 v[76:79], v[116:119], v[212:215], v[76:79]
	v_mfma_f32_16x16x32_bf16 v[72:75], v[132:135], v[212:215], v[72:75]
	v_mfma_f32_16x16x32_bf16 v[124:127], v[136:139], v[184:187], v[124:127]
	v_mfma_f32_16x16x32_bf16 v[120:123], v[144:147], v[184:187], v[120:123]
	v_mfma_f32_16x16x32_bf16 v[100:103], v[136:139], v[192:195], v[100:103]
	v_mfma_f32_16x16x32_bf16 v[96:99], v[144:147], v[192:195], v[96:99]
	v_mfma_f32_16x16x32_bf16 v[84:87], v[136:139], v[200:203], v[84:87]
	v_mfma_f32_16x16x32_bf16 v[80:83], v[144:147], v[200:203], v[80:83]
	v_mfma_f32_16x16x32_bf16 v[68:71], v[136:139], v[208:211], v[68:71]
	v_mfma_f32_16x16x32_bf16 v[64:67], v[144:147], v[208:211], v[64:67]
	v_mfma_f32_16x16x32_bf16 v[124:127], v[140:143], v[188:191], v[124:127]
	v_mfma_f32_16x16x32_bf16 v[120:123], v[180:183], v[188:191], v[120:123]
	v_mfma_f32_16x16x32_bf16 v[100:103], v[140:143], v[196:199], v[100:103]
	v_mfma_f32_16x16x32_bf16 v[96:99], v[180:183], v[196:199], v[96:99]
	v_mfma_f32_16x16x32_bf16 v[84:87], v[140:143], v[204:207], v[84:87]
	v_mfma_f32_16x16x32_bf16 v[80:83], v[180:183], v[204:207], v[80:83]
	v_mfma_f32_16x16x32_bf16 v[68:71], v[140:143], v[212:215], v[68:71]
	v_mfma_f32_16x16x32_bf16 v[64:67], v[180:183], v[212:215], v[64:67]
	s_barrier
; #define PG8_STAGE(bufoff, gbase, voff) do { _Pragma("unroll") for (int _i = 0; _i < 2; ++_i) \
;         __builtin_amdgcn_global_load_lds((const unsigned*)((const char*)(gbase) + (voff)[_i]), (PG8_LAS unsigned*)(lds + (bufoff) + ldsw + _i * 8192), 16, 0, 0); } while (0)
; #define PG8_LDA(dst, b, h) do { _Pragma("unroll") for (int m = 0; m < 4; ++m) _Pragma("unroll") for (int k = 0; k < 2; ++k) dst[m][k] = *(const PG8_LAS bf16x8*)(lds + PG8_SA(b, h) + aoff + m * 2048 + k * 1024); } while (0)
; #define PG8_MMA(ai, bj, At, Bt) do { __builtin_amdgcn_s_setprio(1); _Pragma("unroll") for (int m = 0; m < 4; ++m) _Pragma("unroll") for (int n = 0; n < 2; ++n) _Pragma("unroll") for (int k = 0; k < 2; ++k) \
;         acc[ai][bj][m][n] = __builtin_amdgcn_mfma_f32_16x16x32_bf16(Bt[n][k], At[m][k], acc[ai][bj][m][n], 0, 0, 0); __builtin_amdgcn_s_setprio(0); } while (0)
; #define PG8_WAIT_V(n) asm volatile("s_waitcnt vmcnt(" #n ")" ::: "memory")
; #define PG8_WAIT_L(n) asm volatile("s_waitcnt lgkmcnt(" #n ")" ::: "memory")
; #define PG8_BAR __builtin_amdgcn_s_barrier()
; #define PG8_SCHED __builtin_amdgcn_sched_barrier(0)
; template <class Epi, class Sched, bool ALIGN_EPI = false, bool SP2 = false>
; __device__ __forceinline__ void gemm_phase(PG8_LAS unsigned char* lds, const Gemm g, const Sched& S, const Epi& E) {
;     ...
;             PG8_LDA(At, 1, 1); PG8_STAGE(PG8_SB(1, 0), b3, voffB); PG8_STAGE(PG8_SB(1, 1), b3 + hstep, voffB); PG8_STAGE(PG8_SA(1, 0), a3, voffA);
;             PG8_WAIT_V(8); PG8_WAIT_L(0); PG8_BAR; PG8_MMA(1, 0, At, B0); PG8_MMA(1, 1, At, B1); PG8_BAR; PG8_SCHED;
	s_add_i32 s10, s54, s14
	v_lshl_add_u64 v[216:217], v[216:217], 0, s[96:97]
	s_mov_b32 m0, s10
	ds_read_b128 v[184:187], v239 offset:49152
	ds_read_b128 v[188:191], v239 offset:50176
	ds_read_b128 v[192:195], v239 offset:51200
	ds_read_b128 v[196:199], v239 offset:52224
	ds_read_b128 v[200:203], v239 offset:53248
	ds_read_b128 v[204:207], v239 offset:54272
	ds_read_b128 v[208:211], v239 offset:55296
	ds_read_b128 v[212:215], v239 offset:56320
	global_load_lds_dwordx4 v[216:217], off
	s_add_i32 m0, s10, 0x2000
	s_add_u32 s8, s8, 0x40080
	v_lshl_add_u64 v[216:217], v[218:219], 0, s[96:97]
	s_addc_u32 s9, s9, 0
	s_add_i32 s10, s55, s14
	global_load_lds_dwordx4 v[216:217], off
	v_lshl_add_u64 v[216:217], s[8:9], 0, v[156:157]
	s_mov_b32 m0, s10
	s_nop 0
	global_load_lds_dwordx4 v[216:217], off
	v_lshl_add_u64 v[216:217], s[8:9], 0, v[170:171]
	s_add_i32 m0, s10, 0x2000
	s_nop 0
	global_load_lds_dwordx4 v[216:217], off
	v_lshl_add_u64 v[216:217], v[220:221], 0, s[96:97]
	s_mov_b32 m0, s19
	s_nop 0
	global_load_lds_dwordx4 v[216:217], off
	v_lshl_add_u64 v[216:217], v[222:223], 0, s[96:97]
	s_mov_b32 m0, s20
	s_nop 0
	global_load_lds_dwordx4 v[216:217], off
	s_waitcnt vmcnt(8)
	s_waitcnt lgkmcnt(0)
	s_barrier
	s_waitcnt lgkmcnt(0)
	v_mfma_f32_16x16x32_bf16 v[60:63], v[104:107], v[184:187], v[60:63]
	v_mfma_f32_16x16x32_bf16 v[56:59], v[128:131], v[184:187], v[56:59]
	v_mfma_f32_16x16x32_bf16 v[44:47], v[104:107], v[192:195], v[44:47]
	v_mfma_f32_16x16x32_bf16 v[40:43], v[128:131], v[192:195], v[40:43]
	v_mfma_f32_16x16x32_bf16 v[28:31], v[104:107], v[200:203], v[28:31]
	v_mfma_f32_16x16x32_bf16 v[24:27], v[128:131], v[200:203], v[24:27]
	v_mfma_f32_16x16x32_bf16 v[12:15], v[104:107], v[208:211], v[12:15]
	v_mfma_f32_16x16x32_bf16 v[8:11], v[128:131], v[208:211], v[8:11]
	v_mfma_f32_16x16x32_bf16 v[60:63], v[116:119], v[188:191], v[60:63]
	v_mfma_f32_16x16x32_bf16 v[56:59], v[132:135], v[188:191], v[56:59]
	v_mfma_f32_16x16x32_bf16 v[44:47], v[116:119], v[196:199], v[44:47]
	v_mfma_f32_16x16x32_bf16 v[40:43], v[132:135], v[196:199], v[40:43]
	v_mfma_f32_16x16x32_bf16 v[28:31], v[116:119], v[204:207], v[28:31]
	v_mfma_f32_16x16x32_bf16 v[24:27], v[132:135], v[204:207], v[24:27]
	v_mfma_f32_16x16x32_bf16 v[12:15], v[116:119], v[212:215], v[12:15]
	v_mfma_f32_16x16x32_bf16 v[8:11], v[132:135], v[212:215], v[8:11]
	v_mfma_f32_16x16x32_bf16 v[52:55], v[136:139], v[184:187], v[52:55]
	v_mfma_f32_16x16x32_bf16 v[48:51], v[144:147], v[184:187], v[48:51]
	v_mfma_f32_16x16x32_bf16 v[36:39], v[136:139], v[192:195], v[36:39]
	v_mfma_f32_16x16x32_bf16 v[32:35], v[144:147], v[192:195], v[32:35]
	v_mfma_f32_16x16x32_bf16 v[20:23], v[136:139], v[200:203], v[20:23]
	v_mfma_f32_16x16x32_bf16 v[16:19], v[144:147], v[200:203], v[16:19]
	v_mfma_f32_16x16x32_bf16 v[4:7], v[136:139], v[208:211], v[4:7]
	v_mfma_f32_16x16x32_bf16 v[0:3], v[144:147], v[208:211], v[0:3]
	v_mfma_f32_16x16x32_bf16 v[52:55], v[140:143], v[188:191], v[52:55]
	v_mfma_f32_16x16x32_bf16 v[48:51], v[180:183], v[188:191], v[48:51]
	v_mfma_f32_16x16x32_bf16 v[36:39], v[140:143], v[196:199], v[36:39]
	v_mfma_f32_16x16x32_bf16 v[32:35], v[180:183], v[196:199], v[32:35]
	v_mfma_f32_16x16x32_bf16 v[20:23], v[140:143], v[204:207], v[20:23]
	v_mfma_f32_16x16x32_bf16 v[16:19], v[180:183], v[204:207], v[16:19]
	v_mfma_f32_16x16x32_bf16 v[4:7], v[140:143], v[212:215], v[4:7]
	v_mfma_f32_16x16x32_bf16 v[0:3], v[180:183], v[212:215], v[0:3]
	s_barrier
	s_add_i32 s47, s47, 2
	s_add_u32 s6, s6, 0x100
	s_addc_u32 s7, s7, 0
	s_add_u32 s35, s35, 0x100
	s_addc_u32 s45, s45, 0
	s_cmp_gt_u32 s47, 13
	s_cbranch_scc0 .LBB0_356
	s_and_b64 vcc, exec, s[42:43]
	s_cbranch_vccz .LBB0_359
	s_barrier

; #define PG8_STAGE(bufoff, gbase, voff) do { _Pragma("unroll") for (int _i = 0; _i < 2; ++_i) \
;         __builtin_amdgcn_global_load_lds((const unsigned*)((const char*)(gbase) + (voff)[_i]), (PG8_LAS unsigned*)(lds + (bufoff) + ldsw + _i * 8192), 16, 0, 0); } while (0)
; #define PG8_LDA(dst, b, h) do { _Pragma("unroll") for (int m = 0; m < 4; ++m) _Pragma("unroll") for (int k = 0; k < 2; ++k) dst[m][k] = *(const PG8_LAS bf16x8*)(lds + PG8_SA(b, h) + aoff + m * 2048 + k * 1024); } while (0)
; #define PG8_LDB(dst, b, h) do { _Pragma("unroll") for (int n = 0; n < 2; ++n) _Pragma("unroll") for (int k = 0; k < 2; ++k) dst[n][k] = *(const PG8_LAS bf16x8*)(lds + PG8_SB(b, h) + boff + n * 2048 + k * 1024); } while (0)
; #define PG8_MMA(ai, bj, At, Bt) do { __builtin_amdgcn_s_setprio(1); _Pragma("unroll") for (int m = 0; m < 4; ++m) _Pragma("unroll") for (int n = 0; n < 2; ++n) _Pragma("unroll") for (int k = 0; k < 2; ++k) \
;         acc[ai][bj][m][n] = __builtin_amdgcn_mfma_f32_16x16x32_bf16(Bt[n][k], At[m][k], acc[ai][bj][m][n], 0, 0, 0); __builtin_amdgcn_s_setprio(0); } while (0)
; #define PG8_WAIT_V(n) asm volatile("s_waitcnt vmcnt(" #n ")" ::: "memory")
; #define PG8_WAIT_L(n) asm volatile("s_waitcnt lgkmcnt(" #n ")" ::: "memory")
; #define PG8_BAR __builtin_amdgcn_s_barrier()
; #define PG8_SCHED __builtin_amdgcn_sched_barrier(0)
; template <class Epi, class Sched, bool ALIGN_EPI = false, bool SP2 = false>
; __device__ __forceinline__ void gemm_phase(PG8_LAS unsigned char* lds, const Gemm g, const Sched& S, const Epi& E) {
;     ...
;             const bool last = (t == nt - 2);
;             const char* a1 = cA + (size_t)(t + 1) * kstep;
;             const char* a2 = last ? nA : cA + (size_t)(t + 2) * kstep; const char* b2 = last ? nB : cB + (size_t)(t + 2) * kstep;
;             const char* a3 = a2 + kstep; const char* b3 = b2 + kstep;
;             if (last && has_next) S.a_ready(nxt);
;             if constexpr (SP2) {
;             PG8_LDB(B0, 0, 0); PG8_LDB(B1, 0, 1); PG8_SCHED; PG8_LDA(At, 0, 0); PG8_STAGE(PG8_SA(1, 1), a1 + hstep, voffA);
;             PG8_WAIT_V(8); PG8_WAIT_L(0); PG8_BAR; PG8_MMA(0, 0, At, B0); PG8_MMA(0, 1, At, B1); PG8_BAR; PG8_SCHED;
;             PG8_LDA(At, 0, 1); PG8_STAGE(PG8_SB(0, 0), b2, voffB); PG8_STAGE(PG8_SB(0, 1), b2 + hstep, voffB); PG8_STAGE(PG8_SA(0, 0), a2, voffA);
.LBB0_399:
	s_add_u32 s12, s10, 0xfffc0080
	s_addc_u32 s13, s11, -1
	s_add_i32 s51, 0, 0x10000
	s_cmp_eq_u32 s50, 12
	s_cselect_b32 s15, s41, s13
	s_cselect_b32 s14, s46, s12
	v_add_u32_e32 v146, s51, v149
	s_cselect_b32 s13, s9, s49
	s_cselect_b32 s12, s47, s48
	s_add_i32 s54, 0, 0x14000
	ds_read_b128 v[138:141], v146
	ds_read_b128 v[142:145], v146 offset:1024
	ds_read_b128 v[168:171], v146 offset:2048
	ds_read_b128 v[172:175], v146 offset:3072
	v_add_u32_e32 v146, s54, v149
	ds_read_b128 v[176:179], v146
	ds_read_b128 v[180:183], v146 offset:1024
	ds_read_b128 v[184:187], v146 offset:2048
	ds_read_b128 v[188:191], v146 offset:3072
	v_lshl_add_u64 v[146:147], s[10:11], 0, v[134:135]
	s_add_i32 m0, s25, 0xc000
	ds_read_b128 v[192:195], v152
	ds_read_b128 v[196:199], v152 offset:1024
	ds_read_b128 v[200:203], v152 offset:2048
	ds_read_b128 v[204:207], v152 offset:3072
	ds_read_b128 v[208:211], v152 offset:4096
	ds_read_b128 v[212:215], v152 offset:5120
	ds_read_b128 v[216:219], v152 offset:6144
	ds_read_b128 v[220:223], v152 offset:7168
	global_load_lds_dwordx4 v[146:147], off
	v_lshl_add_u64 v[146:147], s[10:11], 0, v[136:137]
	s_add_i32 m0, s25, 0xe000
	s_nop 0
	global_load_lds_dwordx4 v[146:147], off
	s_waitcnt vmcnt(8)
	s_waitcnt lgkmcnt(0)
	s_barrier
	s_waitcnt lgkmcnt(0)
	v_mfma_f32_16x16x32_bf16 v[124:127], v[138:141], v[192:195], v[124:127]
	v_mfma_f32_16x16x32_bf16 v[120:123], v[168:171], v[192:195], v[120:123]
	v_mfma_f32_16x16x32_bf16 v[108:111], v[138:141], v[200:203], v[108:111]
	v_mfma_f32_16x16x32_bf16 v[104:107], v[168:171], v[200:203], v[104:107]
	v_mfma_f32_16x16x32_bf16 v[92:95], v[138:141], v[208:211], v[92:95]
	v_mfma_f32_16x16x32_bf16 v[88:91], v[168:171], v[208:211], v[88:91]
	v_mfma_f32_16x16x32_bf16 v[76:79], v[138:141], v[216:219], v[76:79]
	v_mfma_f32_16x16x32_bf16 v[72:75], v[168:171], v[216:219], v[72:75]
	v_mfma_f32_16x16x32_bf16 v[124:127], v[142:145], v[196:199], v[124:127]
	v_mfma_f32_16x16x32_bf16 v[120:123], v[172:175], v[196:199], v[120:123]
	v_mfma_f32_16x16x32_bf16 v[108:111], v[142:145], v[204:207], v[108:111]
	v_mfma_f32_16x16x32_bf16 v[104:107], v[172:175], v[204:207], v[104:107]
	v_mfma_f32_16x16x32_bf16 v[92:95], v[142:145], v[212:215], v[92:95]
	v_mfma_f32_16x16x32_bf16 v[88:91], v[172:175], v[212:215], v[88:91]
	v_mfma_f32_16x16x32_bf16 v[76:79], v[142:145], v[220:223], v[76:79]
	v_mfma_f32_16x16x32_bf16 v[72:75], v[172:175], v[220:223], v[72:75]
	v_mfma_f32_16x16x32_bf16 v[116:119], v[176:179], v[192:195], v[116:119]
	v_mfma_f32_16x16x32_bf16 v[112:115], v[184:187], v[192:195], v[112:115]
	v_mfma_f32_16x16x32_bf16 v[100:103], v[176:179], v[200:203], v[100:103]
	v_mfma_f32_16x16x32_bf16 v[96:99], v[184:187], v[200:203], v[96:99]
	v_mfma_f32_16x16x32_bf16 v[84:87], v[176:179], v[208:211], v[84:87]
	v_mfma_f32_16x16x32_bf16 v[80:83], v[184:187], v[208:211], v[80:83]
	v_mfma_f32_16x16x32_bf16 v[68:71], v[176:179], v[216:219], v[68:71]
	v_mfma_f32_16x16x32_bf16 v[64:67], v[184:187], v[216:219], v[64:67]
	v_mfma_f32_16x16x32_bf16 v[116:119], v[180:183], v[196:199], v[116:119]
	v_mfma_f32_16x16x32_bf16 v[112:115], v[188:191], v[196:199], v[112:115]
	v_mfma_f32_16x16x32_bf16 v[100:103], v[180:183], v[204:207], v[100:103]
	v_mfma_f32_16x16x32_bf16 v[96:99], v[188:191], v[204:207], v[96:99]
	v_mfma_f32_16x16x32_bf16 v[84:87], v[180:183], v[212:215], v[84:87]
	v_mfma_f32_16x16x32_bf16 v[80:83], v[188:191], v[212:215], v[80:83]
	v_mfma_f32_16x16x32_bf16 v[68:71], v[180:183], v[220:223], v[68:71]
	v_mfma_f32_16x16x32_bf16 v[64:67], v[188:191], v[220:223], v[64:67]
	s_barrier
	s_add_i32 s51, s51, s21
	v_lshl_add_u64 v[146:147], s[12:13], 0, v[156:157]
	s_mov_b32 m0, s51
	ds_read_b128 v[192:195], v152 offset:16384
	ds_read_b128 v[196:199], v152 offset:17408
	ds_read_b128 v[200:203], v152 offset:18432
	ds_read_b128 v[204:207], v152 offset:19456
	ds_read_b128 v[208:211], v152 offset:20480
	ds_read_b128 v[212:215], v152 offset:21504
	ds_read_b128 v[216:219], v152 offset:22528
	ds_read_b128 v[220:223], v152 offset:23552
	global_load_lds_dwordx4 v[146:147], off
	s_add_i32 m0, s51, 0x2000
	s_add_u32 s52, s12, 0x40000
	v_lshl_add_u64 v[154:155], s[12:13], 0, v[128:129]
	s_addc_u32 s53, s13, 0
	s_add_i32 s51, s54, s21
	global_load_lds_dwordx4 v[154:155], off
	v_lshl_add_u64 v[224:225], s[52:53], 0, v[156:157]
	s_mov_b32 m0, s51
	v_lshl_add_u64 v[226:227], s[14:15], 0, v[130:131]
	global_load_lds_dwordx4 v[224:225], off
	v_lshl_add_u64 v[224:225], s[52:53], 0, v[128:129]
	s_add_i32 m0, s51, 0x2000
	s_nop 0
	global_load_lds_dwordx4 v[224:225], off
	v_lshl_add_u64 v[224:225], s[14:15], 0, v[132:133]
	s_mov_b32 m0, s25
	s_nop 0
	global_load_lds_dwordx4 v[224:225], off
	s_mov_b32 m0, s26
	s_nop 0
	global_load_lds_dwordx4 v[226:227], off
	s_waitcnt vmcnt(8)
	s_waitcnt lgkmcnt(0)
	s_barrier
; #define PG8_STAGE(bufoff, gbase, voff) do { _Pragma("unroll") for (int _i = 0; _i < 2; ++_i) \
;         __builtin_amdgcn_global_load_lds((const unsigned*)((const char*)(gbase) + (voff)[_i]), (PG8_LAS unsigned*)(lds + (bufoff) + ldsw + _i * 8192), 16, 0, 0); } while (0)
; #define PG8_LDA(dst, b, h) do { _Pragma("unroll") for (int m = 0; m < 4; ++m) _Pragma("unroll") for (int k = 0; k < 2; ++k) dst[m][k] = *(const PG8_LAS bf16x8*)(lds + PG8_SA(b, h) + aoff + m * 2048 + k * 1024); } while (0)
; #define PG8_LDB(dst, b, h) do { _Pragma("unroll") for (int n = 0; n < 2; ++n) _Pragma("unroll") for (int k = 0; k < 2; ++k) dst[n][k] = *(const PG8_LAS bf16x8*)(lds + PG8_SB(b, h) + boff + n * 2048 + k * 1024); } while (0)
; #define PG8_MMA(ai, bj, At, Bt) do { __builtin_amdgcn_s_setprio(1); _Pragma("unroll") for (int m = 0; m < 4; ++m) _Pragma("unroll") for (int n = 0; n < 2; ++n) _Pragma("unroll") for (int k = 0; k < 2; ++k) \
;         acc[ai][bj][m][n] = __builtin_amdgcn_mfma_f32_16x16x32_bf16(Bt[n][k], At[m][k], acc[ai][bj][m][n], 0, 0, 0); __builtin_amdgcn_s_setprio(0); } while (0)
; #define PG8_WAIT_V(n) asm volatile("s_waitcnt vmcnt(" #n ")" ::: "memory")
; #define PG8_WAIT_L(n) asm volatile("s_waitcnt lgkmcnt(" #n ")" ::: "memory")
; #define PG8_BAR __builtin_amdgcn_s_barrier()
; #define PG8_SCHED __builtin_amdgcn_sched_barrier(0)
; template <class Epi, class Sched, bool ALIGN_EPI = false, bool SP2 = false>
; __device__ __forceinline__ void gemm_phase(PG8_LAS unsigned char* lds, const Gemm g, const Sched& S, const Epi& E) {
;     ...
;             PG8_WAIT_V(8); PG8_WAIT_L(0); PG8_BAR; PG8_MMA(1, 0, At, B0); PG8_MMA(1, 1, At, B1); PG8_BAR; PG8_SCHED;
;             PG8_LDB(B0, 1, 0); PG8_LDB(B1, 1, 1); PG8_SCHED; PG8_LDA(At, 1, 0); PG8_STAGE(PG8_SA(0, 1), a2 + hstep, voffA);
;             PG8_WAIT_V(8); PG8_WAIT_L(0); PG8_BAR; PG8_MMA(0, 0, At, B0); PG8_MMA(0, 1, At, B1); PG8_BAR; PG8_SCHED;
	s_waitcnt lgkmcnt(0)
	v_mfma_f32_16x16x32_bf16 v[60:63], v[138:141], v[192:195], v[60:63]
	v_mfma_f32_16x16x32_bf16 v[56:59], v[168:171], v[192:195], v[56:59]
	v_mfma_f32_16x16x32_bf16 v[44:47], v[138:141], v[200:203], v[44:47]
	v_mfma_f32_16x16x32_bf16 v[40:43], v[168:171], v[200:203], v[40:43]
	v_mfma_f32_16x16x32_bf16 v[28:31], v[138:141], v[208:211], v[28:31]
	v_mfma_f32_16x16x32_bf16 v[24:27], v[168:171], v[208:211], v[24:27]
	v_mfma_f32_16x16x32_bf16 v[12:15], v[138:141], v[216:219], v[12:15]
	v_mfma_f32_16x16x32_bf16 v[8:11], v[168:171], v[216:219], v[8:11]
	v_mfma_f32_16x16x32_bf16 v[60:63], v[142:145], v[196:199], v[60:63]
	v_mfma_f32_16x16x32_bf16 v[56:59], v[172:175], v[196:199], v[56:59]
	v_mfma_f32_16x16x32_bf16 v[44:47], v[142:145], v[204:207], v[44:47]
	v_mfma_f32_16x16x32_bf16 v[40:43], v[172:175], v[204:207], v[40:43]
	v_mfma_f32_16x16x32_bf16 v[28:31], v[142:145], v[212:215], v[28:31]
	v_mfma_f32_16x16x32_bf16 v[24:27], v[172:175], v[212:215], v[24:27]
	v_mfma_f32_16x16x32_bf16 v[12:15], v[142:145], v[220:223], v[12:15]
	v_mfma_f32_16x16x32_bf16 v[8:11], v[172:175], v[220:223], v[8:11]
	v_mfma_f32_16x16x32_bf16 v[52:55], v[176:179], v[192:195], v[52:55]
	v_mfma_f32_16x16x32_bf16 v[48:51], v[184:187], v[192:195], v[48:51]
	v_mfma_f32_16x16x32_bf16 v[36:39], v[176:179], v[200:203], v[36:39]
	v_mfma_f32_16x16x32_bf16 v[32:35], v[184:187], v[200:203], v[32:35]
	v_mfma_f32_16x16x32_bf16 v[20:23], v[176:179], v[208:211], v[20:23]
	v_mfma_f32_16x16x32_bf16 v[16:19], v[184:187], v[208:211], v[16:19]
	v_mfma_f32_16x16x32_bf16 v[4:7], v[176:179], v[216:219], v[4:7]
	v_mfma_f32_16x16x32_bf16 v[0:3], v[184:187], v[216:219], v[0:3]
	v_mfma_f32_16x16x32_bf16 v[52:55], v[180:183], v[196:199], v[52:55]
	v_mfma_f32_16x16x32_bf16 v[48:51], v[188:191], v[196:199], v[48:51]
	v_mfma_f32_16x16x32_bf16 v[36:39], v[180:183], v[204:207], v[36:39]
	v_mfma_f32_16x16x32_bf16 v[32:35], v[188:191], v[204:207], v[32:35]
	v_mfma_f32_16x16x32_bf16 v[20:23], v[180:183], v[212:215], v[20:23]
	v_mfma_f32_16x16x32_bf16 v[16:19], v[188:191], v[212:215], v[16:19]
	v_mfma_f32_16x16x32_bf16 v[4:7], v[180:183], v[220:223], v[4:7]
	v_mfma_f32_16x16x32_bf16 v[0:3], v[188:191], v[220:223], v[0:3]
	s_barrier
	s_add_i32 s51, 0, 0x18000
	v_add_u32_e32 v153, s51, v149
	s_add_i32 s52, 0, 0x1c000
	ds_read_b128 v[138:141], v153
	ds_read_b128 v[142:145], v153 offset:1024
	ds_read_b128 v[168:171], v153 offset:2048
	ds_read_b128 v[172:175], v153 offset:3072
	v_add_u32_e32 v153, s52, v149
	ds_read_b128 v[176:179], v153
	ds_read_b128 v[180:183], v153 offset:1024
	ds_read_b128 v[184:187], v153 offset:2048
	ds_read_b128 v[188:191], v153 offset:3072
	s_add_u32 s14, s14, 0x40000
	s_addc_u32 s15, s15, 0
	s_mov_b32 m0, s27
	v_lshl_add_u64 v[228:229], s[14:15], 0, v[132:133]
	ds_read_b128 v[192:195], v152 offset:32768
	ds_read_b128 v[196:199], v152 offset:33792
	ds_read_b128 v[200:203], v152 offset:34816
	ds_read_b128 v[204:207], v152 offset:35840
	ds_read_b128 v[208:211], v152 offset:36864
	ds_read_b128 v[212:215], v152 offset:37888
	ds_read_b128 v[216:219], v152 offset:38912
	ds_read_b128 v[220:223], v152 offset:39936
	global_load_lds_dwordx4 v[228:229], off
	v_lshl_add_u64 v[228:229], s[14:15], 0, v[130:131]
	s_mov_b32 m0, s28
	s_nop 0
	global_load_lds_dwordx4 v[228:229], off
	s_waitcnt vmcnt(8)
	s_waitcnt lgkmcnt(0)
	s_barrier
	s_waitcnt lgkmcnt(0)
	v_mfma_f32_16x16x32_bf16 v[124:127], v[138:141], v[192:195], v[124:127]
	v_mfma_f32_16x16x32_bf16 v[120:123], v[168:171], v[192:195], v[120:123]
	v_mfma_f32_16x16x32_bf16 v[108:111], v[138:141], v[200:203], v[108:111]
	v_mfma_f32_16x16x32_bf16 v[104:107], v[168:171], v[200:203], v[104:107]
	v_mfma_f32_16x16x32_bf16 v[92:95], v[138:141], v[208:211], v[92:95]
	v_mfma_f32_16x16x32_bf16 v[88:91], v[168:171], v[208:211], v[88:91]
	v_mfma_f32_16x16x32_bf16 v[76:79], v[138:141], v[216:219], v[76:79]
	v_mfma_f32_16x16x32_bf16 v[72:75], v[168:171], v[216:219], v[72:75]
	v_mfma_f32_16x16x32_bf16 v[124:127], v[142:145], v[196:199], v[124:127]
	v_mfma_f32_16x16x32_bf16 v[120:123], v[172:175], v[196:199], v[120:123]
	v_mfma_f32_16x16x32_bf16 v[108:111], v[142:145], v[204:207], v[108:111]
	v_mfma_f32_16x16x32_bf16 v[104:107], v[172:175], v[204:207], v[104:107]
	v_mfma_f32_16x16x32_bf16 v[92:95], v[142:145], v[212:215], v[92:95]
	v_mfma_f32_16x16x32_bf16 v[88:91], v[172:175], v[212:215], v[88:91]
	v_mfma_f32_16x16x32_bf16 v[76:79], v[142:145], v[220:223], v[76:79]
	v_mfma_f32_16x16x32_bf16 v[72:75], v[172:175], v[220:223], v[72:75]
	v_mfma_f32_16x16x32_bf16 v[116:119], v[176:179], v[192:195], v[116:119]
	v_mfma_f32_16x16x32_bf16 v[112:115], v[184:187], v[192:195], v[112:115]
	v_mfma_f32_16x16x32_bf16 v[100:103], v[176:179], v[200:203], v[100:103]
	v_mfma_f32_16x16x32_bf16 v[96:99], v[184:187], v[200:203], v[96:99]
	v_mfma_f32_16x16x32_bf16 v[84:87], v[176:179], v[208:211], v[84:87]
	v_mfma_f32_16x16x32_bf16 v[80:83], v[184:187], v[208:211], v[80:83]
	v_mfma_f32_16x16x32_bf16 v[68:71], v[176:179], v[216:219], v[68:71]
	v_mfma_f32_16x16x32_bf16 v[64:67], v[184:187], v[216:219], v[64:67]
	v_mfma_f32_16x16x32_bf16 v[116:119], v[180:183], v[196:199], v[116:119]
	v_mfma_f32_16x16x32_bf16 v[112:115], v[188:191], v[196:199], v[112:115]
	v_mfma_f32_16x16x32_bf16 v[100:103], v[180:183], v[204:207], v[100:103]
	v_mfma_f32_16x16x32_bf16 v[96:99], v[188:191], v[204:207], v[96:99]
	v_mfma_f32_16x16x32_bf16 v[84:87], v[180:183], v[212:215], v[84:87]
	v_mfma_f32_16x16x32_bf16 v[80:83], v[188:191], v[212:215], v[80:83]
	v_mfma_f32_16x16x32_bf16 v[68:71], v[180:183], v[220:223], v[68:71]
	v_mfma_f32_16x16x32_bf16 v[64:67], v[188:191], v[220:223], v[64:67]
	s_barrier
; #define PG8_STAGE(bufoff, gbase, voff) do { _Pragma("unroll") for (int _i = 0; _i < 2; ++_i) \
;         __builtin_amdgcn_global_load_lds((const unsigned*)((const char*)(gbase) + (voff)[_i]), (PG8_LAS unsigned*)(lds + (bufoff) + ldsw + _i * 8192), 16, 0, 0); } while (0)
; #define PG8_LDA(dst, b, h) do { _Pragma("unroll") for (int m = 0; m < 4; ++m) _Pragma("unroll") for (int k = 0; k < 2; ++k) dst[m][k] = *(const PG8_LAS bf16x8*)(lds + PG8_SA(b, h) + aoff + m * 2048 + k * 1024); } while (0)
; #define PG8_MMA(ai, bj, At, Bt) do { __builtin_amdgcn_s_setprio(1); _Pragma("unroll") for (int m = 0; m < 4; ++m) _Pragma("unroll") for (int n = 0; n < 2; ++n) _Pragma("unroll") for (int k = 0; k < 2; ++k) \
;         acc[ai][bj][m][n] = __builtin_amdgcn_mfma_f32_16x16x32_bf16(Bt[n][k], At[m][k], acc[ai][bj][m][n], 0, 0, 0); __builtin_amdgcn_s_setprio(0); } while (0)
; #define PG8_WAIT_V(n) asm volatile("s_waitcnt vmcnt(" #n ")" ::: "memory")
; #define PG8_WAIT_L(n) asm volatile("s_waitcnt lgkmcnt(" #n ")" ::: "memory")
; #define PG8_BAR __builtin_amdgcn_s_barrier()
; #define PG8_SCHED __builtin_amdgcn_sched_barrier(0)
; template <class Epi, class Sched, bool ALIGN_EPI = false, bool SP2 = false>
; __device__ __forceinline__ void gemm_phase(PG8_LAS unsigned char* lds, const Gemm g, const Sched& S, const Epi& E) {
;     ...
;             PG8_LDA(At, 1, 1); PG8_STAGE(PG8_SB(1, 0), b3, voffB); PG8_STAGE(PG8_SB(1, 1), b3 + hstep, voffB); PG8_STAGE(PG8_SA(1, 0), a3, voffA);
;             PG8_WAIT_V(8); PG8_WAIT_L(0); PG8_BAR; PG8_MMA(1, 0, At, B0); PG8_MMA(1, 1, At, B1); PG8_BAR; PG8_SCHED;
	s_add_i32 s14, s51, s21
	v_lshl_add_u64 v[146:147], v[146:147], 0, s[96:97]
	s_mov_b32 m0, s14
	ds_read_b128 v[192:195], v152 offset:49152
	ds_read_b128 v[196:199], v152 offset:50176
	ds_read_b128 v[200:203], v152 offset:51200
	ds_read_b128 v[204:207], v152 offset:52224
	ds_read_b128 v[208:211], v152 offset:53248
	ds_read_b128 v[212:215], v152 offset:54272
	ds_read_b128 v[216:219], v152 offset:55296
	ds_read_b128 v[220:223], v152 offset:56320
	global_load_lds_dwordx4 v[146:147], off
	s_add_i32 m0, s14, 0x2000
	s_add_u32 s12, s12, 0x40080
	v_lshl_add_u64 v[146:147], v[154:155], 0, s[96:97]
	s_addc_u32 s13, s13, 0
	s_add_i32 s14, s52, s21
	global_load_lds_dwordx4 v[146:147], off
	v_lshl_add_u64 v[146:147], s[12:13], 0, v[156:157]
	s_mov_b32 m0, s14
	s_nop 0
	global_load_lds_dwordx4 v[146:147], off
	v_lshl_add_u64 v[146:147], s[12:13], 0, v[128:129]
	s_add_i32 m0, s14, 0x2000
	s_nop 0
	global_load_lds_dwordx4 v[146:147], off
	v_lshl_add_u64 v[146:147], v[224:225], 0, s[96:97]
	s_mov_b32 m0, s29
	s_nop 0
	global_load_lds_dwordx4 v[146:147], off
	v_lshl_add_u64 v[146:147], v[226:227], 0, s[96:97]
	s_mov_b32 m0, s30
	s_nop 0
	global_load_lds_dwordx4 v[146:147], off
	s_waitcnt vmcnt(8)
	s_waitcnt lgkmcnt(0)
	s_barrier
	s_waitcnt lgkmcnt(0)
	v_mfma_f32_16x16x32_bf16 v[60:63], v[138:141], v[192:195], v[60:63]
	v_mfma_f32_16x16x32_bf16 v[56:59], v[168:171], v[192:195], v[56:59]
	v_mfma_f32_16x16x32_bf16 v[44:47], v[138:141], v[200:203], v[44:47]
	v_mfma_f32_16x16x32_bf16 v[40:43], v[168:171], v[200:203], v[40:43]
	v_mfma_f32_16x16x32_bf16 v[28:31], v[138:141], v[208:211], v[28:31]
	v_mfma_f32_16x16x32_bf16 v[24:27], v[168:171], v[208:211], v[24:27]
	v_mfma_f32_16x16x32_bf16 v[12:15], v[138:141], v[216:219], v[12:15]
	v_mfma_f32_16x16x32_bf16 v[8:11], v[168:171], v[216:219], v[8:11]
	v_mfma_f32_16x16x32_bf16 v[60:63], v[142:145], v[196:199], v[60:63]
	v_mfma_f32_16x16x32_bf16 v[56:59], v[172:175], v[196:199], v[56:59]
	v_mfma_f32_16x16x32_bf16 v[44:47], v[142:145], v[204:207], v[44:47]
	v_mfma_f32_16x16x32_bf16 v[40:43], v[172:175], v[204:207], v[40:43]
	v_mfma_f32_16x16x32_bf16 v[28:31], v[142:145], v[212:215], v[28:31]
	v_mfma_f32_16x16x32_bf16 v[24:27], v[172:175], v[212:215], v[24:27]
	v_mfma_f32_16x16x32_bf16 v[12:15], v[142:145], v[220:223], v[12:15]
	v_mfma_f32_16x16x32_bf16 v[8:11], v[172:175], v[220:223], v[8:11]
	v_mfma_f32_16x16x32_bf16 v[52:55], v[176:179], v[192:195], v[52:55]
	v_mfma_f32_16x16x32_bf16 v[48:51], v[184:187], v[192:195], v[48:51]
	v_mfma_f32_16x16x32_bf16 v[36:39], v[176:179], v[200:203], v[36:39]
	v_mfma_f32_16x16x32_bf16 v[32:35], v[184:187], v[200:203], v[32:35]
	v_mfma_f32_16x16x32_bf16 v[20:23], v[176:179], v[208:211], v[20:23]
	v_mfma_f32_16x16x32_bf16 v[16:19], v[184:187], v[208:211], v[16:19]
	v_mfma_f32_16x16x32_bf16 v[4:7], v[176:179], v[216:219], v[4:7]
	v_mfma_f32_16x16x32_bf16 v[0:3], v[184:187], v[216:219], v[0:3]
	v_mfma_f32_16x16x32_bf16 v[52:55], v[180:183], v[196:199], v[52:55]
	v_mfma_f32_16x16x32_bf16 v[48:51], v[188:191], v[196:199], v[48:51]
	v_mfma_f32_16x16x32_bf16 v[36:39], v[180:183], v[204:207], v[36:39]
	v_mfma_f32_16x16x32_bf16 v[32:35], v[188:191], v[204:207], v[32:35]
	v_mfma_f32_16x16x32_bf16 v[20:23], v[180:183], v[212:215], v[20:23]
	v_mfma_f32_16x16x32_bf16 v[16:19], v[188:191], v[212:215], v[16:19]
	v_mfma_f32_16x16x32_bf16 v[4:7], v[180:183], v[220:223], v[4:7]
	v_mfma_f32_16x16x32_bf16 v[0:3], v[188:191], v[220:223], v[0:3]
	s_barrier
	s_add_i32 s50, s50, 2
	s_add_u32 s10, s10, 0x100
	s_addc_u32 s11, s11, 0
	s_add_u32 s48, s48, 0x100
	s_addc_u32 s49, s49, 0
	s_cmp_gt_u32 s50, 13
	s_cbranch_scc0 .LBB0_399
	s_and_b64 vcc, exec, s[6:7]
	s_cbranch_vccz .LBB0_402
	s_barrier
